# same as v46 with 20480 items (20 per wave) moved to the FFN-in tail
# speedup vs baseline: 1.0046x; 1.0008x over previous
.LBB0_464:
	s_min_i32 s5, s84, 0x80
	v_readlane_b32 s0, v254, 0
	s_waitcnt vmcnt(0)
	v_lshrrev_b32_e32 v2, 6, v0
	s_mov_b32 s2, s0
	s_cmp_ge_i32 s0, s5
	s_mul_i32 s0, s0, 2
	v_add3_u32 v3, v2, s0, -1
	s_cselect_b64 vcc, -1, 0
	s_sub_i32 s0, s2, s5
	s_mul_i32 s4, s5, 2
	s_lshl_b32 s0, s0, 3
	s_add_i32 s0, s0, s4
	v_readlane_b32 s1, v254, 1
	v_add_u32_e32 v2, s0, v2
	v_add_u32_e32 v31, -64, v0
	s_movk_i32 s7, 0x80
	v_cmp_gt_u32_e64 s[0:1], s7, v31
	v_cndmask_b32_e32 v30, v3, v2, vcc
	s_mov_b32 s6, 0x13200
	s_or_b64 s[0:1], vcc, s[0:1]
	v_cmp_gt_i32_e32 vcc, s6, v30
	s_movk_i32 s3, 0x80
	s_and_b64 s[6:7], s[0:1], vcc
	s_and_saveexec_b64 s[0:1], s[6:7]
	s_cbranch_execz .LBB0_491
	s_sub_i32 s5, s84, s5
	v_lshlrev_b32_e32 v2, 8, v0
	s_lshl_b32 s33, s5, 3
	v_and_b32_e32 v2, 0x1c000, v2
	s_add_i32 s33, s33, s4
	v_add_u32_e32 v7, 0, v2
	v_lshlrev_b32_e32 v2, 4, v0
	v_and_b32_e32 v24, 0x70, v2
	v_lshlrev_b32_e32 v2, 3, v0
	s_add_u32 s6, s66, 0x8100000
	v_and_b32_e32 v2, 56, v2
	s_addc_u32 s7, s67, 0
	v_mul_u32_u24_e32 v6, 0x84, v2
	v_lshlrev_b32_e32 v2, 1, v2
	v_mov_b32_e32 v3, 0
	s_add_u32 s8, s66, 0x93400
	v_lshl_add_u64 v[12:13], s[66:67], 0, v[2:3]
	s_addc_u32 s9, s67, 0
	s_mov_b64 s[12:13], 0x6100000
	s_add_u32 s10, s66, 0xbc000
	v_lshl_add_u64 v[8:9], v[12:13], 0, s[12:13]
	s_mov_b64 s[12:13], 0x5100000
	s_mov_b64 s[4:5], 0x12d00000
	s_addc_u32 s11, s67, 0
	v_lshl_add_u64 v[10:11], v[12:13], 0, s[12:13]
	s_mov_b64 s[12:13], 0x4100000
	v_lshl_add_u64 v[4:5], v[12:13], 0, s[4:5]
	v_lshl_add_u64 v[12:13], v[12:13], 0, s[12:13]
	s_add_u32 s12, s66, 0x100000
	s_addc_u32 s13, s67, 0
	v_readlane_b32 s36, v254, 20
	v_lshrrev_b32_e32 v31, 3, v1
	s_add_u32 s14, s66, 0x8b400
	v_readlane_b32 s40, v254, 24
	v_readlane_b32 s41, v254, 25
	v_add_u32_e32 v26, v7, v24
	v_mul_u32_u24_e32 v27, 0x84, v31
	s_addc_u32 s15, s67, 0
	v_readlane_b32 s42, v254, 26
	v_readlane_b32 s43, v254, 27
	v_readlane_b32 s44, v254, 28
	v_readlane_b32 s45, v254, 29
	v_readlane_b32 s46, v254, 30
	v_readlane_b32 s47, v254, 31
	v_readlane_b32 s48, v254, 32
	v_readlane_b32 s49, v254, 33
	v_readlane_b32 s50, v254, 34
	v_readlane_b32 s51, v254, 35
	s_mov_b64 s[20:21], s[40:41]
	v_lshlrev_b32_e32 v2, 2, v31
	v_lshrrev_b32_e32 v1, 1, v1
	v_and_b32_e32 v40, 1, v0
	s_add_u32 s16, s66, 0xb4000
	v_mov_b32_e32 v25, v3
	v_readlane_b32 s37, v254, 21
	v_readlane_b32 s38, v254, 22
	v_readlane_b32 s39, v254, 23
	s_mov_b64 s[24:25], s[44:45]
	s_mov_b64 s[26:27], s[46:47]
	s_mov_b64 s[28:29], s[48:49]
	s_mov_b64 s[30:31], s[50:51]
	v_add_u32_e32 v44, v26, v27
	v_or_b32_e32 v32, 8, v31
	v_or_b32_e32 v33, 16, v31
	v_or_b32_e32 v34, 24, v31
	v_or_b32_e32 v35, 32, v31
	v_or_b32_e32 v36, 40, v31
	v_or_b32_e32 v37, 48, v31
	v_or_b32_e32 v38, 56, v31
	v_add3_u32 v39, v7, v6, v2
	v_lshlrev_b32_e32 v6, 5, v40
	v_lshl_add_u32 v41, v1, 2, v7
	v_mul_u32_u24_e32 v42, 0x1080, v40
	v_mov_b32_e32 v7, v3
	v_cmp_eq_u32_e64 s[4:5], 0, v40
	s_addc_u32 s17, s67, 0
	v_lshl_add_u64 v[14:15], s[60:61], 0, v[24:25]
	v_lshl_add_u64 v[16:17], s[54:55], 0, v[24:25]
	s_mov_b64 s[22:23], s[42:43]
	v_lshl_add_u64 v[18:19], s[30:31], 0, v[24:25]
	v_lshl_add_u64 v[20:21], s[26:27], 0, v[24:25]
	v_lshl_add_u64 v[22:23], s[24:25], 0, v[24:25]
	v_lshl_add_u64 v[24:25], s[28:29], 0, v[24:25]
	v_lshlrev_b32_e32 v43, 5, v30
	s_lshl_b32 s34, s33, 5
	s_mov_b64 s[18:19], 0
	s_movk_i32 s35, 0x3fff
	s_movk_i32 s36, 0x4fff
	s_movk_i32 s37, 0x5fff
	s_movk_i32 s38, 0x7fff
	s_mov_b32 s39, 0x12bff
	v_add_u32_e32 v45, 0x420, v44
	v_add_u32_e32 v46, 0x428, v44
	v_add_u32_e32 v47, 0x840, v44
	v_add_u32_e32 v48, 0x848, v44
	v_add_u32_e32 v49, 0xc60, v44
	v_add_u32_e32 v50, 0xc68, v44
	s_mov_b32 s40, 0xffff0000
	s_mov_b32 s41, 0xbe83
	s_movk_i32 s42, 0x2b0
	s_movk_i32 s43, 0x2a80
	s_mov_b32 s44, 0x42fe0000
	s_mov_b32 s45, 0xc0c0500
	s_mov_b32 s46, 0x131ff
	v_add_u32_e32 v51, 0x1080, v44
	v_add_u32_e32 v52, 0x1088, v44
	v_add_u32_e32 v53, 0x14a0, v44
	v_add_u32_e32 v54, 0x14a8, v44
	v_add_u32_e32 v55, 0x18c0, v44
	s_branch .LBB0_468

.LBB0_1906:
	s_waitcnt vmcnt(0)
	s_mov_b32 s2, s86
	s_barrier
	v_readlane_b32 s94, v254, 0
	s_nop 3
	s_cmpk_lt_u32 s94, 0x80
	s_cbranch_scc1 .Lwf_done
	v_readlane_b32 s96, v254, 2
	v_readlane_b32 s97, v254, 3
	v_readfirstlane_b32 s95, v0
	s_nop 3
	s_sub_u32 s96, s96, 0x28
	s_subb_u32 s97, s97, 0
	s_load_dwordx2 s[100:101], s[96:97], 0x0
	s_lshr_b32 s95, s95, 6
	s_sub_u32 s94, s94, 0x80
	s_lshl_b32 s94, s94, 3
	s_add_u32 s94, s94, s95
	s_add_u32 s94, s94, 0x600
	v_and_b32_e32 v2, 63, v0
	v_lshrrev_b32_e32 v3, 3, v2
	v_and_b32_e32 v4, 7, v2
	v_lshlrev_b32_e32 v5, 14, v3
	v_lshl_add_u32 v5, v4, 4, v5
	v_add_u32_e32 v6, 0x0, v5
	v_add_u32_e32 v7, 0x20000, v5
	v_add_u32_e32 v8, 0x40000, v5
	v_add_u32_e32 v9, 0x60000, v5
	v_add_u32_e32 v10, 0x80000, v5
	v_add_u32_e32 v11, 0xa0000, v5
	v_add_u32_e32 v12, 0xc0000, v5
	v_add_u32_e32 v13, 0xe0000, v5
	s_lshl_b32 s95, s95, 14
	v_mul_u32_u24_e32 v14, 0x84, v3
	v_lshl_add_u32 v14, v4, 4, v14
	v_add_u32_e32 v14, s95, v14
	v_mul_u32_u24_e32 v15, 0x420, v4
	v_lshl_add_u32 v15, v3, 2, v15
	v_add_u32_e32 v15, s95, v15
	v_mul_u32_u24_e32 v16, 0x5600, v3
	v_lshl_add_u32 v16, v4, 4, v16
	v_add_u32_e32 v17, 0x2b000, v16
	v_add_u32_e32 v18, 0x56000, v16
	v_add_u32_e32 v19, 0x81000, v16
	s_waitcnt lgkmcnt(0)
	s_mov_b32 s95, s94
	s_lshr_b32 vcc_lo, s95, 7
	s_and_b32 vcc_hi, s95, 0x7f
	s_lshl_b32 vcc_lo, vcc_lo, 20
	s_lshl_b32 vcc_hi, vcc_hi, 7
	s_add_u32 s96, s100, vcc_lo
	s_addc_u32 s97, s101, 0
	s_add_u32 s96, s96, vcc_hi
	s_addc_u32 s97, s97, 0
	global_load_dwordx4 v[20:23], v6, s[96:97]
	global_load_dwordx4 v[24:27], v7, s[96:97]
	global_load_dwordx4 v[28:31], v8, s[96:97]
	global_load_dwordx4 v[32:35], v9, s[96:97]
	global_load_dwordx4 v[36:39], v10, s[96:97]
	global_load_dwordx4 v[40:43], v11, s[96:97]
	global_load_dwordx4 v[44:47], v12, s[96:97]
	global_load_dwordx4 v[48:51], v13, s[96:97]
	s_add_u32 s95, s94, 0x400
	s_lshr_b32 vcc_lo, s95, 7
	s_and_b32 vcc_hi, s95, 0x7f
	s_lshl_b32 vcc_lo, vcc_lo, 20
	s_lshl_b32 vcc_hi, vcc_hi, 7
	s_add_u32 s96, s100, vcc_lo
	s_addc_u32 s97, s101, 0
	s_add_u32 s96, s96, vcc_hi
	s_addc_u32 s97, s97, 0
	global_load_dwordx4 v[100:103], v6, s[96:97]
	global_load_dwordx4 v[104:107], v7, s[96:97]
	global_load_dwordx4 v[108:111], v8, s[96:97]
	global_load_dwordx4 v[112:115], v9, s[96:97]
	global_load_dwordx4 v[116:119], v10, s[96:97]
	global_load_dwordx4 v[120:123], v11, s[96:97]
	global_load_dwordx4 v[124:127], v12, s[96:97]
	global_load_dwordx4 v[128:131], v13, s[96:97]
	s_waitcnt vmcnt(15)
	ds_write_b32 v14, v20 offset:0
	ds_write_b32 v14, v21 offset:4
	ds_write_b32 v14, v22 offset:8
	ds_write_b32 v14, v23 offset:12
	s_waitcnt vmcnt(14)
	ds_write_b32 v14, v24 offset:1056
	ds_write_b32 v14, v25 offset:1060
	ds_write_b32 v14, v26 offset:1064
	ds_write_b32 v14, v27 offset:1068
	s_waitcnt vmcnt(13)
	ds_write_b32 v14, v28 offset:2112
	ds_write_b32 v14, v29 offset:2116
	ds_write_b32 v14, v30 offset:2120
	ds_write_b32 v14, v31 offset:2124
	s_waitcnt vmcnt(12)
	ds_write_b32 v14, v32 offset:3168
	ds_write_b32 v14, v33 offset:3172
	ds_write_b32 v14, v34 offset:3176
	ds_write_b32 v14, v35 offset:3180
	s_waitcnt vmcnt(11)
	ds_write_b32 v14, v36 offset:4224
	ds_write_b32 v14, v37 offset:4228
	ds_write_b32 v14, v38 offset:4232
	ds_write_b32 v14, v39 offset:4236
	s_waitcnt vmcnt(10)
	ds_write_b32 v14, v40 offset:5280
	ds_write_b32 v14, v41 offset:5284
	ds_write_b32 v14, v42 offset:5288
	ds_write_b32 v14, v43 offset:5292
	s_waitcnt vmcnt(9)
	ds_write_b32 v14, v44 offset:6336
	ds_write_b32 v14, v45 offset:6340
	ds_write_b32 v14, v46 offset:6344
	ds_write_b32 v14, v47 offset:6348
	s_waitcnt vmcnt(8)
	ds_write_b32 v14, v48 offset:7392
	ds_write_b32 v14, v49 offset:7396
	ds_write_b32 v14, v50 offset:7400
	ds_write_b32 v14, v51 offset:7404
	s_add_u32 s95, s94, 0x800
	s_lshr_b32 vcc_lo, s95, 7
	s_and_b32 vcc_hi, s95, 0x7f
	s_lshl_b32 vcc_lo, vcc_lo, 20
	s_lshl_b32 vcc_hi, vcc_hi, 7
	s_add_u32 s96, s100, vcc_lo
	s_addc_u32 s97, s101, 0
	s_add_u32 s96, s96, vcc_hi
	s_addc_u32 s97, s97, 0
	global_load_dwordx4 v[20:23], v6, s[96:97]
	global_load_dwordx4 v[24:27], v7, s[96:97]
	global_load_dwordx4 v[28:31], v8, s[96:97]
	global_load_dwordx4 v[32:35], v9, s[96:97]
	global_load_dwordx4 v[36:39], v10, s[96:97]
	global_load_dwordx4 v[40:43], v11, s[96:97]
	global_load_dwordx4 v[44:47], v12, s[96:97]
	global_load_dwordx4 v[48:51], v13, s[96:97]
	ds_read2_b32 v[52:53], v15 offset0:0 offset1:33
	ds_read2_b32 v[54:55], v15 offset0:66 offset1:99
	ds_read2_b32 v[56:57], v15 offset0:132 offset1:165
	ds_read2_b32 v[58:59], v15 offset0:198 offset1:231
	ds_read2_b32 v[60:61], v15 offset0:8 offset1:41
	ds_read2_b32 v[62:63], v15 offset0:74 offset1:107
	ds_read2_b32 v[64:65], v15 offset0:140 offset1:173
	ds_read2_b32 v[66:67], v15 offset0:206 offset1:239
	ds_read2_b32 v[68:69], v15 offset0:16 offset1:49
	ds_read2_b32 v[70:71], v15 offset0:82 offset1:115
	ds_read2_b32 v[72:73], v15 offset0:148 offset1:181
	ds_read2_b32 v[74:75], v15 offset0:214 offset1:247
	ds_read2_b32 v[76:77], v15 offset0:24 offset1:57
	ds_read2_b32 v[78:79], v15 offset0:90 offset1:123
	ds_read2_b32 v[80:81], v15 offset0:156 offset1:189
	ds_read2_b32 v[82:83], v15 offset0:222 offset1:255
	s_mov_b32 s95, s94
	s_lshr_b32 vcc_lo, s95, 7
	s_and_b32 vcc_hi, s95, 0x7f
	s_mul_i32 vcc_hi, vcc_hi, 0xac000
	s_lshl_b32 vcc_lo, vcc_lo, 7
	s_add_u32 s98, s66, 0x12d00000
	s_addc_u32 s99, s67, 0
	s_add_u32 s98, s98, vcc_hi
	s_addc_u32 s99, s99, 0
	s_add_u32 s98, s98, vcc_lo
	s_addc_u32 s99, s99, 0
	s_waitcnt lgkmcnt(0)
	v_cvt_pk_bf16_f32 v84, v52, v53
	v_cvt_pk_bf16_f32 v85, v54, v55
	v_cvt_pk_bf16_f32 v86, v56, v57
	v_cvt_pk_bf16_f32 v87, v58, v59
	v_cvt_pk_bf16_f32 v88, v60, v61
	v_cvt_pk_bf16_f32 v89, v62, v63
	v_cvt_pk_bf16_f32 v90, v64, v65
	v_cvt_pk_bf16_f32 v91, v66, v67
	v_cvt_pk_bf16_f32 v92, v68, v69
	v_cvt_pk_bf16_f32 v93, v70, v71
	v_cvt_pk_bf16_f32 v94, v72, v73
	v_cvt_pk_bf16_f32 v95, v74, v75
	v_cvt_pk_bf16_f32 v96, v76, v77
	v_cvt_pk_bf16_f32 v97, v78, v79
	v_cvt_pk_bf16_f32 v98, v80, v81
	v_cvt_pk_bf16_f32 v99, v82, v83
	global_store_dwordx4 v16, v[84:87], s[98:99]
	global_store_dwordx4 v17, v[88:91], s[98:99]
	global_store_dwordx4 v18, v[92:95], s[98:99]
	global_store_dwordx4 v19, v[96:99], s[98:99]
	s_waitcnt vmcnt(19)
	ds_write_b32 v14, v100 offset:0
	ds_write_b32 v14, v101 offset:4
	ds_write_b32 v14, v102 offset:8
	ds_write_b32 v14, v103 offset:12
	s_waitcnt vmcnt(18)
	ds_write_b32 v14, v104 offset:1056
	ds_write_b32 v14, v105 offset:1060
	ds_write_b32 v14, v106 offset:1064
	ds_write_b32 v14, v107 offset:1068
	s_waitcnt vmcnt(17)
	ds_write_b32 v14, v108 offset:2112
	ds_write_b32 v14, v109 offset:2116
	ds_write_b32 v14, v110 offset:2120
	ds_write_b32 v14, v111 offset:2124
	s_waitcnt vmcnt(16)
	ds_write_b32 v14, v112 offset:3168
	ds_write_b32 v14, v113 offset:3172
	ds_write_b32 v14, v114 offset:3176
	ds_write_b32 v14, v115 offset:3180
	s_waitcnt vmcnt(15)
	ds_write_b32 v14, v116 offset:4224
	ds_write_b32 v14, v117 offset:4228
	ds_write_b32 v14, v118 offset:4232
	ds_write_b32 v14, v119 offset:4236
	s_waitcnt vmcnt(14)
	ds_write_b32 v14, v120 offset:5280
	ds_write_b32 v14, v121 offset:5284
	ds_write_b32 v14, v122 offset:5288
	ds_write_b32 v14, v123 offset:5292
	s_waitcnt vmcnt(13)
	ds_write_b32 v14, v124 offset:6336
	ds_write_b32 v14, v125 offset:6340
	ds_write_b32 v14, v126 offset:6344
	ds_write_b32 v14, v127 offset:6348
	s_waitcnt vmcnt(12)
	ds_write_b32 v14, v128 offset:7392
	ds_write_b32 v14, v129 offset:7396
	ds_write_b32 v14, v130 offset:7400
	ds_write_b32 v14, v131 offset:7404
	s_add_u32 s95, s94, 0xc00
	s_lshr_b32 vcc_lo, s95, 7
	s_and_b32 vcc_hi, s95, 0x7f
	s_lshl_b32 vcc_lo, vcc_lo, 20
	s_lshl_b32 vcc_hi, vcc_hi, 7
	s_add_u32 s96, s100, vcc_lo
	s_addc_u32 s97, s101, 0
	s_add_u32 s96, s96, vcc_hi
	s_addc_u32 s97, s97, 0
	global_load_dwordx4 v[100:103], v6, s[96:97]
	global_load_dwordx4 v[104:107], v7, s[96:97]
	global_load_dwordx4 v[108:111], v8, s[96:97]
	global_load_dwordx4 v[112:115], v9, s[96:97]
	global_load_dwordx4 v[116:119], v10, s[96:97]
	global_load_dwordx4 v[120:123], v11, s[96:97]
	global_load_dwordx4 v[124:127], v12, s[96:97]
	global_load_dwordx4 v[128:131], v13, s[96:97]
	ds_read2_b32 v[52:53], v15 offset0:0 offset1:33
	ds_read2_b32 v[54:55], v15 offset0:66 offset1:99
	ds_read2_b32 v[56:57], v15 offset0:132 offset1:165
	ds_read2_b32 v[58:59], v15 offset0:198 offset1:231
	ds_read2_b32 v[60:61], v15 offset0:8 offset1:41
	ds_read2_b32 v[62:63], v15 offset0:74 offset1:107
	ds_read2_b32 v[64:65], v15 offset0:140 offset1:173
	ds_read2_b32 v[66:67], v15 offset0:206 offset1:239
	ds_read2_b32 v[68:69], v15 offset0:16 offset1:49
	ds_read2_b32 v[70:71], v15 offset0:82 offset1:115
	ds_read2_b32 v[72:73], v15 offset0:148 offset1:181
	ds_read2_b32 v[74:75], v15 offset0:214 offset1:247
	ds_read2_b32 v[76:77], v15 offset0:24 offset1:57
	ds_read2_b32 v[78:79], v15 offset0:90 offset1:123
	ds_read2_b32 v[80:81], v15 offset0:156 offset1:189
	ds_read2_b32 v[82:83], v15 offset0:222 offset1:255
	s_add_u32 s95, s94, 0x400
	s_lshr_b32 vcc_lo, s95, 7
	s_and_b32 vcc_hi, s95, 0x7f
	s_mul_i32 vcc_hi, vcc_hi, 0xac000
	s_lshl_b32 vcc_lo, vcc_lo, 7
	s_add_u32 s98, s66, 0x12d00000
	s_addc_u32 s99, s67, 0
	s_add_u32 s98, s98, vcc_hi
	s_addc_u32 s99, s99, 0
	s_add_u32 s98, s98, vcc_lo
	s_addc_u32 s99, s99, 0
	s_waitcnt lgkmcnt(0)
	v_cvt_pk_bf16_f32 v84, v52, v53
	v_cvt_pk_bf16_f32 v85, v54, v55
	v_cvt_pk_bf16_f32 v86, v56, v57
	v_cvt_pk_bf16_f32 v87, v58, v59
	v_cvt_pk_bf16_f32 v88, v60, v61
	v_cvt_pk_bf16_f32 v89, v62, v63
	v_cvt_pk_bf16_f32 v90, v64, v65
	v_cvt_pk_bf16_f32 v91, v66, v67
	v_cvt_pk_bf16_f32 v92, v68, v69
	v_cvt_pk_bf16_f32 v93, v70, v71
	v_cvt_pk_bf16_f32 v94, v72, v73
	v_cvt_pk_bf16_f32 v95, v74, v75
	v_cvt_pk_bf16_f32 v96, v76, v77
	v_cvt_pk_bf16_f32 v97, v78, v79
	v_cvt_pk_bf16_f32 v98, v80, v81
	v_cvt_pk_bf16_f32 v99, v82, v83
	global_store_dwordx4 v16, v[84:87], s[98:99]
	global_store_dwordx4 v17, v[88:91], s[98:99]
	global_store_dwordx4 v18, v[92:95], s[98:99]
	global_store_dwordx4 v19, v[96:99], s[98:99]
	s_waitcnt vmcnt(23)
	ds_write_b32 v14, v20 offset:0
	ds_write_b32 v14, v21 offset:4
	ds_write_b32 v14, v22 offset:8
	ds_write_b32 v14, v23 offset:12
	s_waitcnt vmcnt(22)
	ds_write_b32 v14, v24 offset:1056
	ds_write_b32 v14, v25 offset:1060
	ds_write_b32 v14, v26 offset:1064
	ds_write_b32 v14, v27 offset:1068
	s_waitcnt vmcnt(21)
	ds_write_b32 v14, v28 offset:2112
	ds_write_b32 v14, v29 offset:2116
	ds_write_b32 v14, v30 offset:2120
	ds_write_b32 v14, v31 offset:2124
	s_waitcnt vmcnt(20)
	ds_write_b32 v14, v32 offset:3168
	ds_write_b32 v14, v33 offset:3172
	ds_write_b32 v14, v34 offset:3176
	ds_write_b32 v14, v35 offset:3180
	s_waitcnt vmcnt(19)
	ds_write_b32 v14, v36 offset:4224
	ds_write_b32 v14, v37 offset:4228
	ds_write_b32 v14, v38 offset:4232
	ds_write_b32 v14, v39 offset:4236
	s_waitcnt vmcnt(18)
	ds_write_b32 v14, v40 offset:5280
	ds_write_b32 v14, v41 offset:5284
	ds_write_b32 v14, v42 offset:5288
	ds_write_b32 v14, v43 offset:5292
	s_waitcnt vmcnt(17)
	ds_write_b32 v14, v44 offset:6336
	ds_write_b32 v14, v45 offset:6340
	ds_write_b32 v14, v46 offset:6344
	ds_write_b32 v14, v47 offset:6348
	s_waitcnt vmcnt(16)
	ds_write_b32 v14, v48 offset:7392
	ds_write_b32 v14, v49 offset:7396
	ds_write_b32 v14, v50 offset:7400
	ds_write_b32 v14, v51 offset:7404
	s_add_u32 s95, s94, 0x1000
	s_lshr_b32 vcc_lo, s95, 7
	s_and_b32 vcc_hi, s95, 0x7f
	s_lshl_b32 vcc_lo, vcc_lo, 20
	s_lshl_b32 vcc_hi, vcc_hi, 7
	s_add_u32 s96, s100, vcc_lo
	s_addc_u32 s97, s101, 0
	s_add_u32 s96, s96, vcc_hi
	s_addc_u32 s97, s97, 0
	global_load_dwordx4 v[20:23], v6, s[96:97]
	global_load_dwordx4 v[24:27], v7, s[96:97]
	global_load_dwordx4 v[28:31], v8, s[96:97]
	global_load_dwordx4 v[32:35], v9, s[96:97]
	global_load_dwordx4 v[36:39], v10, s[96:97]
	global_load_dwordx4 v[40:43], v11, s[96:97]
	global_load_dwordx4 v[44:47], v12, s[96:97]
	global_load_dwordx4 v[48:51], v13, s[96:97]
	ds_read2_b32 v[52:53], v15 offset0:0 offset1:33
	ds_read2_b32 v[54:55], v15 offset0:66 offset1:99
	ds_read2_b32 v[56:57], v15 offset0:132 offset1:165
	ds_read2_b32 v[58:59], v15 offset0:198 offset1:231
	ds_read2_b32 v[60:61], v15 offset0:8 offset1:41
	ds_read2_b32 v[62:63], v15 offset0:74 offset1:107
	ds_read2_b32 v[64:65], v15 offset0:140 offset1:173
	ds_read2_b32 v[66:67], v15 offset0:206 offset1:239
	ds_read2_b32 v[68:69], v15 offset0:16 offset1:49
	ds_read2_b32 v[70:71], v15 offset0:82 offset1:115
	ds_read2_b32 v[72:73], v15 offset0:148 offset1:181
	ds_read2_b32 v[74:75], v15 offset0:214 offset1:247
	ds_read2_b32 v[76:77], v15 offset0:24 offset1:57
	ds_read2_b32 v[78:79], v15 offset0:90 offset1:123
	ds_read2_b32 v[80:81], v15 offset0:156 offset1:189
	ds_read2_b32 v[82:83], v15 offset0:222 offset1:255
	s_add_u32 s95, s94, 0x800
	s_lshr_b32 vcc_lo, s95, 7
	s_and_b32 vcc_hi, s95, 0x7f
	s_mul_i32 vcc_hi, vcc_hi, 0xac000
	s_lshl_b32 vcc_lo, vcc_lo, 7
	s_add_u32 s98, s66, 0x12d00000
	s_addc_u32 s99, s67, 0
	s_add_u32 s98, s98, vcc_hi
	s_addc_u32 s99, s99, 0
	s_add_u32 s98, s98, vcc_lo
	s_addc_u32 s99, s99, 0
	s_waitcnt lgkmcnt(0)
	v_cvt_pk_bf16_f32 v84, v52, v53
	v_cvt_pk_bf16_f32 v85, v54, v55
	v_cvt_pk_bf16_f32 v86, v56, v57
	v_cvt_pk_bf16_f32 v87, v58, v59
	v_cvt_pk_bf16_f32 v88, v60, v61
	v_cvt_pk_bf16_f32 v89, v62, v63
	v_cvt_pk_bf16_f32 v90, v64, v65
	v_cvt_pk_bf16_f32 v91, v66, v67
	v_cvt_pk_bf16_f32 v92, v68, v69
	v_cvt_pk_bf16_f32 v93, v70, v71
	v_cvt_pk_bf16_f32 v94, v72, v73
	v_cvt_pk_bf16_f32 v95, v74, v75
	v_cvt_pk_bf16_f32 v96, v76, v77
	v_cvt_pk_bf16_f32 v97, v78, v79
	v_cvt_pk_bf16_f32 v98, v80, v81
	v_cvt_pk_bf16_f32 v99, v82, v83
	global_store_dwordx4 v16, v[84:87], s[98:99]
	global_store_dwordx4 v17, v[88:91], s[98:99]
	global_store_dwordx4 v18, v[92:95], s[98:99]
	global_store_dwordx4 v19, v[96:99], s[98:99]
	s_waitcnt vmcnt(23)
	ds_write_b32 v14, v100 offset:0
	ds_write_b32 v14, v101 offset:4
	ds_write_b32 v14, v102 offset:8
	ds_write_b32 v14, v103 offset:12
	s_waitcnt vmcnt(22)
	ds_write_b32 v14, v104 offset:1056
	ds_write_b32 v14, v105 offset:1060
	ds_write_b32 v14, v106 offset:1064
	ds_write_b32 v14, v107 offset:1068
	s_waitcnt vmcnt(21)
	ds_write_b32 v14, v108 offset:2112
	ds_write_b32 v14, v109 offset:2116
	ds_write_b32 v14, v110 offset:2120
	ds_write_b32 v14, v111 offset:2124
	s_waitcnt vmcnt(20)
	ds_write_b32 v14, v112 offset:3168
	ds_write_b32 v14, v113 offset:3172
	ds_write_b32 v14, v114 offset:3176
	ds_write_b32 v14, v115 offset:3180
	s_waitcnt vmcnt(19)
	ds_write_b32 v14, v116 offset:4224
	ds_write_b32 v14, v117 offset:4228
	ds_write_b32 v14, v118 offset:4232
	ds_write_b32 v14, v119 offset:4236
	s_waitcnt vmcnt(18)
	ds_write_b32 v14, v120 offset:5280
	ds_write_b32 v14, v121 offset:5284
	ds_write_b32 v14, v122 offset:5288
	ds_write_b32 v14, v123 offset:5292
	s_waitcnt vmcnt(17)
	ds_write_b32 v14, v124 offset:6336
	ds_write_b32 v14, v125 offset:6340
	ds_write_b32 v14, v126 offset:6344
	ds_write_b32 v14, v127 offset:6348
	s_waitcnt vmcnt(16)
	ds_write_b32 v14, v128 offset:7392
	ds_write_b32 v14, v129 offset:7396
	ds_write_b32 v14, v130 offset:7400
	ds_write_b32 v14, v131 offset:7404
	s_add_u32 s95, s94, 0x1400
	s_lshr_b32 vcc_lo, s95, 7
	s_and_b32 vcc_hi, s95, 0x7f
	s_lshl_b32 vcc_lo, vcc_lo, 20
	s_lshl_b32 vcc_hi, vcc_hi, 7
	s_add_u32 s96, s100, vcc_lo
	s_addc_u32 s97, s101, 0
	s_add_u32 s96, s96, vcc_hi
	s_addc_u32 s97, s97, 0
	global_load_dwordx4 v[100:103], v6, s[96:97]
	global_load_dwordx4 v[104:107], v7, s[96:97]
	global_load_dwordx4 v[108:111], v8, s[96:97]
	global_load_dwordx4 v[112:115], v9, s[96:97]
	global_load_dwordx4 v[116:119], v10, s[96:97]
	global_load_dwordx4 v[120:123], v11, s[96:97]
	global_load_dwordx4 v[124:127], v12, s[96:97]
	global_load_dwordx4 v[128:131], v13, s[96:97]
	ds_read2_b32 v[52:53], v15 offset0:0 offset1:33
	ds_read2_b32 v[54:55], v15 offset0:66 offset1:99
	ds_read2_b32 v[56:57], v15 offset0:132 offset1:165
	ds_read2_b32 v[58:59], v15 offset0:198 offset1:231
	ds_read2_b32 v[60:61], v15 offset0:8 offset1:41
	ds_read2_b32 v[62:63], v15 offset0:74 offset1:107
	ds_read2_b32 v[64:65], v15 offset0:140 offset1:173
	ds_read2_b32 v[66:67], v15 offset0:206 offset1:239
	ds_read2_b32 v[68:69], v15 offset0:16 offset1:49
	ds_read2_b32 v[70:71], v15 offset0:82 offset1:115
	ds_read2_b32 v[72:73], v15 offset0:148 offset1:181
	ds_read2_b32 v[74:75], v15 offset0:214 offset1:247
	ds_read2_b32 v[76:77], v15 offset0:24 offset1:57
	ds_read2_b32 v[78:79], v15 offset0:90 offset1:123
	ds_read2_b32 v[80:81], v15 offset0:156 offset1:189
	ds_read2_b32 v[82:83], v15 offset0:222 offset1:255
	s_add_u32 s95, s94, 0xc00
	s_lshr_b32 vcc_lo, s95, 7
	s_and_b32 vcc_hi, s95, 0x7f
	s_mul_i32 vcc_hi, vcc_hi, 0xac000
	s_lshl_b32 vcc_lo, vcc_lo, 7
	s_add_u32 s98, s66, 0x12d00000
	s_addc_u32 s99, s67, 0
	s_add_u32 s98, s98, vcc_hi
	s_addc_u32 s99, s99, 0
	s_add_u32 s98, s98, vcc_lo
	s_addc_u32 s99, s99, 0
	s_waitcnt lgkmcnt(0)
	v_cvt_pk_bf16_f32 v84, v52, v53
	v_cvt_pk_bf16_f32 v85, v54, v55
	v_cvt_pk_bf16_f32 v86, v56, v57
	v_cvt_pk_bf16_f32 v87, v58, v59
	v_cvt_pk_bf16_f32 v88, v60, v61
	v_cvt_pk_bf16_f32 v89, v62, v63
	v_cvt_pk_bf16_f32 v90, v64, v65
	v_cvt_pk_bf16_f32 v91, v66, v67
	v_cvt_pk_bf16_f32 v92, v68, v69
	v_cvt_pk_bf16_f32 v93, v70, v71
	v_cvt_pk_bf16_f32 v94, v72, v73
	v_cvt_pk_bf16_f32 v95, v74, v75
	v_cvt_pk_bf16_f32 v96, v76, v77
	v_cvt_pk_bf16_f32 v97, v78, v79
	v_cvt_pk_bf16_f32 v98, v80, v81
	v_cvt_pk_bf16_f32 v99, v82, v83
	global_store_dwordx4 v16, v[84:87], s[98:99]
	global_store_dwordx4 v17, v[88:91], s[98:99]
	global_store_dwordx4 v18, v[92:95], s[98:99]
	global_store_dwordx4 v19, v[96:99], s[98:99]
	s_waitcnt vmcnt(23)
	ds_write_b32 v14, v20 offset:0
	ds_write_b32 v14, v21 offset:4
	ds_write_b32 v14, v22 offset:8
	ds_write_b32 v14, v23 offset:12
	s_waitcnt vmcnt(22)
	ds_write_b32 v14, v24 offset:1056
	ds_write_b32 v14, v25 offset:1060
	ds_write_b32 v14, v26 offset:1064
	ds_write_b32 v14, v27 offset:1068
	s_waitcnt vmcnt(21)
	ds_write_b32 v14, v28 offset:2112
	ds_write_b32 v14, v29 offset:2116
	ds_write_b32 v14, v30 offset:2120
	ds_write_b32 v14, v31 offset:2124
	s_waitcnt vmcnt(20)
	ds_write_b32 v14, v32 offset:3168
	ds_write_b32 v14, v33 offset:3172
	ds_write_b32 v14, v34 offset:3176
	ds_write_b32 v14, v35 offset:3180
	s_waitcnt vmcnt(19)
	ds_write_b32 v14, v36 offset:4224
	ds_write_b32 v14, v37 offset:4228
	ds_write_b32 v14, v38 offset:4232
	ds_write_b32 v14, v39 offset:4236
	s_waitcnt vmcnt(18)
	ds_write_b32 v14, v40 offset:5280
	ds_write_b32 v14, v41 offset:5284
	ds_write_b32 v14, v42 offset:5288
	ds_write_b32 v14, v43 offset:5292
	s_waitcnt vmcnt(17)
	ds_write_b32 v14, v44 offset:6336
	ds_write_b32 v14, v45 offset:6340
	ds_write_b32 v14, v46 offset:6344
	ds_write_b32 v14, v47 offset:6348
	s_waitcnt vmcnt(16)
	ds_write_b32 v14, v48 offset:7392
	ds_write_b32 v14, v49 offset:7396
	ds_write_b32 v14, v50 offset:7400
	ds_write_b32 v14, v51 offset:7404
	s_add_u32 s95, s94, 0x1800
	s_lshr_b32 vcc_lo, s95, 7
	s_and_b32 vcc_hi, s95, 0x7f
	s_lshl_b32 vcc_lo, vcc_lo, 20
	s_lshl_b32 vcc_hi, vcc_hi, 7
	s_add_u32 s96, s100, vcc_lo
	s_addc_u32 s97, s101, 0
	s_add_u32 s96, s96, vcc_hi
	s_addc_u32 s97, s97, 0
	global_load_dwordx4 v[20:23], v6, s[96:97]
	global_load_dwordx4 v[24:27], v7, s[96:97]
	global_load_dwordx4 v[28:31], v8, s[96:97]
	global_load_dwordx4 v[32:35], v9, s[96:97]
	global_load_dwordx4 v[36:39], v10, s[96:97]
	global_load_dwordx4 v[40:43], v11, s[96:97]
	global_load_dwordx4 v[44:47], v12, s[96:97]
	global_load_dwordx4 v[48:51], v13, s[96:97]
	ds_read2_b32 v[52:53], v15 offset0:0 offset1:33
	ds_read2_b32 v[54:55], v15 offset0:66 offset1:99
	ds_read2_b32 v[56:57], v15 offset0:132 offset1:165
	ds_read2_b32 v[58:59], v15 offset0:198 offset1:231
	ds_read2_b32 v[60:61], v15 offset0:8 offset1:41
	ds_read2_b32 v[62:63], v15 offset0:74 offset1:107
	ds_read2_b32 v[64:65], v15 offset0:140 offset1:173
	ds_read2_b32 v[66:67], v15 offset0:206 offset1:239
	ds_read2_b32 v[68:69], v15 offset0:16 offset1:49
	ds_read2_b32 v[70:71], v15 offset0:82 offset1:115
	ds_read2_b32 v[72:73], v15 offset0:148 offset1:181
	ds_read2_b32 v[74:75], v15 offset0:214 offset1:247
	ds_read2_b32 v[76:77], v15 offset0:24 offset1:57
	ds_read2_b32 v[78:79], v15 offset0:90 offset1:123
	ds_read2_b32 v[80:81], v15 offset0:156 offset1:189
	ds_read2_b32 v[82:83], v15 offset0:222 offset1:255
	s_add_u32 s95, s94, 0x1000
	s_lshr_b32 vcc_lo, s95, 7
	s_and_b32 vcc_hi, s95, 0x7f
	s_mul_i32 vcc_hi, vcc_hi, 0xac000
	s_lshl_b32 vcc_lo, vcc_lo, 7
	s_add_u32 s98, s66, 0x12d00000
	s_addc_u32 s99, s67, 0
	s_add_u32 s98, s98, vcc_hi
	s_addc_u32 s99, s99, 0
	s_add_u32 s98, s98, vcc_lo
	s_addc_u32 s99, s99, 0
	s_waitcnt lgkmcnt(0)
	v_cvt_pk_bf16_f32 v84, v52, v53
	v_cvt_pk_bf16_f32 v85, v54, v55
	v_cvt_pk_bf16_f32 v86, v56, v57
	v_cvt_pk_bf16_f32 v87, v58, v59
	v_cvt_pk_bf16_f32 v88, v60, v61
	v_cvt_pk_bf16_f32 v89, v62, v63
	v_cvt_pk_bf16_f32 v90, v64, v65
	v_cvt_pk_bf16_f32 v91, v66, v67
	v_cvt_pk_bf16_f32 v92, v68, v69
	v_cvt_pk_bf16_f32 v93, v70, v71
	v_cvt_pk_bf16_f32 v94, v72, v73
	v_cvt_pk_bf16_f32 v95, v74, v75
	v_cvt_pk_bf16_f32 v96, v76, v77
	v_cvt_pk_bf16_f32 v97, v78, v79
	v_cvt_pk_bf16_f32 v98, v80, v81
	v_cvt_pk_bf16_f32 v99, v82, v83
	global_store_dwordx4 v16, v[84:87], s[98:99]
	global_store_dwordx4 v17, v[88:91], s[98:99]
	global_store_dwordx4 v18, v[92:95], s[98:99]
	global_store_dwordx4 v19, v[96:99], s[98:99]
	s_waitcnt vmcnt(23)
	ds_write_b32 v14, v100 offset:0
	ds_write_b32 v14, v101 offset:4
	ds_write_b32 v14, v102 offset:8
	ds_write_b32 v14, v103 offset:12
	s_waitcnt vmcnt(22)
	ds_write_b32 v14, v104 offset:1056
	ds_write_b32 v14, v105 offset:1060
	ds_write_b32 v14, v106 offset:1064
	ds_write_b32 v14, v107 offset:1068
	s_waitcnt vmcnt(21)
	ds_write_b32 v14, v108 offset:2112
	ds_write_b32 v14, v109 offset:2116
	ds_write_b32 v14, v110 offset:2120
	ds_write_b32 v14, v111 offset:2124
	s_waitcnt vmcnt(20)
	ds_write_b32 v14, v112 offset:3168
	ds_write_b32 v14, v113 offset:3172
	ds_write_b32 v14, v114 offset:3176
	ds_write_b32 v14, v115 offset:3180
	s_waitcnt vmcnt(19)
	ds_write_b32 v14, v116 offset:4224
	ds_write_b32 v14, v117 offset:4228
	ds_write_b32 v14, v118 offset:4232
	ds_write_b32 v14, v119 offset:4236
	s_waitcnt vmcnt(18)
	ds_write_b32 v14, v120 offset:5280
	ds_write_b32 v14, v121 offset:5284
	ds_write_b32 v14, v122 offset:5288
	ds_write_b32 v14, v123 offset:5292
	s_waitcnt vmcnt(17)
	ds_write_b32 v14, v124 offset:6336
	ds_write_b32 v14, v125 offset:6340
	ds_write_b32 v14, v126 offset:6344
	ds_write_b32 v14, v127 offset:6348
	s_waitcnt vmcnt(16)
	ds_write_b32 v14, v128 offset:7392
	ds_write_b32 v14, v129 offset:7396
	ds_write_b32 v14, v130 offset:7400
	ds_write_b32 v14, v131 offset:7404
	s_add_u32 s95, s94, 0x1c00
	s_lshr_b32 vcc_lo, s95, 7
	s_and_b32 vcc_hi, s95, 0x7f
	s_lshl_b32 vcc_lo, vcc_lo, 20
	s_lshl_b32 vcc_hi, vcc_hi, 7
	s_add_u32 s96, s100, vcc_lo
	s_addc_u32 s97, s101, 0
	s_add_u32 s96, s96, vcc_hi
	s_addc_u32 s97, s97, 0
	global_load_dwordx4 v[100:103], v6, s[96:97]
	global_load_dwordx4 v[104:107], v7, s[96:97]
	global_load_dwordx4 v[108:111], v8, s[96:97]
	global_load_dwordx4 v[112:115], v9, s[96:97]
	global_load_dwordx4 v[116:119], v10, s[96:97]
	global_load_dwordx4 v[120:123], v11, s[96:97]
	global_load_dwordx4 v[124:127], v12, s[96:97]
	global_load_dwordx4 v[128:131], v13, s[96:97]
	ds_read2_b32 v[52:53], v15 offset0:0 offset1:33
	ds_read2_b32 v[54:55], v15 offset0:66 offset1:99
	ds_read2_b32 v[56:57], v15 offset0:132 offset1:165
	ds_read2_b32 v[58:59], v15 offset0:198 offset1:231
	ds_read2_b32 v[60:61], v15 offset0:8 offset1:41
	ds_read2_b32 v[62:63], v15 offset0:74 offset1:107
	ds_read2_b32 v[64:65], v15 offset0:140 offset1:173
	ds_read2_b32 v[66:67], v15 offset0:206 offset1:239
	ds_read2_b32 v[68:69], v15 offset0:16 offset1:49
	ds_read2_b32 v[70:71], v15 offset0:82 offset1:115
	ds_read2_b32 v[72:73], v15 offset0:148 offset1:181
	ds_read2_b32 v[74:75], v15 offset0:214 offset1:247
	ds_read2_b32 v[76:77], v15 offset0:24 offset1:57
	ds_read2_b32 v[78:79], v15 offset0:90 offset1:123
	ds_read2_b32 v[80:81], v15 offset0:156 offset1:189
	ds_read2_b32 v[82:83], v15 offset0:222 offset1:255
	s_add_u32 s95, s94, 0x1400
	s_lshr_b32 vcc_lo, s95, 7
	s_and_b32 vcc_hi, s95, 0x7f
	s_mul_i32 vcc_hi, vcc_hi, 0xac000
	s_lshl_b32 vcc_lo, vcc_lo, 7
	s_add_u32 s98, s66, 0x12d00000
	s_addc_u32 s99, s67, 0
	s_add_u32 s98, s98, vcc_hi
	s_addc_u32 s99, s99, 0
	s_add_u32 s98, s98, vcc_lo
	s_addc_u32 s99, s99, 0
	s_waitcnt lgkmcnt(0)
	v_cvt_pk_bf16_f32 v84, v52, v53
	v_cvt_pk_bf16_f32 v85, v54, v55
	v_cvt_pk_bf16_f32 v86, v56, v57
	v_cvt_pk_bf16_f32 v87, v58, v59
	v_cvt_pk_bf16_f32 v88, v60, v61
	v_cvt_pk_bf16_f32 v89, v62, v63
	v_cvt_pk_bf16_f32 v90, v64, v65
	v_cvt_pk_bf16_f32 v91, v66, v67
	v_cvt_pk_bf16_f32 v92, v68, v69
	v_cvt_pk_bf16_f32 v93, v70, v71
	v_cvt_pk_bf16_f32 v94, v72, v73
	v_cvt_pk_bf16_f32 v95, v74, v75
	v_cvt_pk_bf16_f32 v96, v76, v77
	v_cvt_pk_bf16_f32 v97, v78, v79
	v_cvt_pk_bf16_f32 v98, v80, v81
	v_cvt_pk_bf16_f32 v99, v82, v83
	global_store_dwordx4 v16, v[84:87], s[98:99]
	global_store_dwordx4 v17, v[88:91], s[98:99]
	global_store_dwordx4 v18, v[92:95], s[98:99]
	global_store_dwordx4 v19, v[96:99], s[98:99]
	s_waitcnt vmcnt(23)
	ds_write_b32 v14, v20 offset:0
	ds_write_b32 v14, v21 offset:4
	ds_write_b32 v14, v22 offset:8
	ds_write_b32 v14, v23 offset:12
	s_waitcnt vmcnt(22)
	ds_write_b32 v14, v24 offset:1056
	ds_write_b32 v14, v25 offset:1060
	ds_write_b32 v14, v26 offset:1064
	ds_write_b32 v14, v27 offset:1068
	s_waitcnt vmcnt(21)
	ds_write_b32 v14, v28 offset:2112
	ds_write_b32 v14, v29 offset:2116
	ds_write_b32 v14, v30 offset:2120
	ds_write_b32 v14, v31 offset:2124
	s_waitcnt vmcnt(20)
	ds_write_b32 v14, v32 offset:3168
	ds_write_b32 v14, v33 offset:3172
	ds_write_b32 v14, v34 offset:3176
	ds_write_b32 v14, v35 offset:3180
	s_waitcnt vmcnt(19)
	ds_write_b32 v14, v36 offset:4224
	ds_write_b32 v14, v37 offset:4228
	ds_write_b32 v14, v38 offset:4232
	ds_write_b32 v14, v39 offset:4236
	s_waitcnt vmcnt(18)
	ds_write_b32 v14, v40 offset:5280
	ds_write_b32 v14, v41 offset:5284
	ds_write_b32 v14, v42 offset:5288
	ds_write_b32 v14, v43 offset:5292
	s_waitcnt vmcnt(17)
	ds_write_b32 v14, v44 offset:6336
	ds_write_b32 v14, v45 offset:6340
	ds_write_b32 v14, v46 offset:6344
	ds_write_b32 v14, v47 offset:6348
	s_waitcnt vmcnt(16)
	ds_write_b32 v14, v48 offset:7392
	ds_write_b32 v14, v49 offset:7396
	ds_write_b32 v14, v50 offset:7400
	ds_write_b32 v14, v51 offset:7404
	s_add_u32 s95, s94, 0x2000
	s_lshr_b32 vcc_lo, s95, 7
	s_and_b32 vcc_hi, s95, 0x7f
	s_lshl_b32 vcc_lo, vcc_lo, 20
	s_lshl_b32 vcc_hi, vcc_hi, 7
	s_add_u32 s96, s100, vcc_lo
	s_addc_u32 s97, s101, 0
	s_add_u32 s96, s96, vcc_hi
	s_addc_u32 s97, s97, 0
	global_load_dwordx4 v[20:23], v6, s[96:97]
	global_load_dwordx4 v[24:27], v7, s[96:97]
	global_load_dwordx4 v[28:31], v8, s[96:97]
	global_load_dwordx4 v[32:35], v9, s[96:97]
	global_load_dwordx4 v[36:39], v10, s[96:97]
	global_load_dwordx4 v[40:43], v11, s[96:97]
	global_load_dwordx4 v[44:47], v12, s[96:97]
	global_load_dwordx4 v[48:51], v13, s[96:97]
	ds_read2_b32 v[52:53], v15 offset0:0 offset1:33
	ds_read2_b32 v[54:55], v15 offset0:66 offset1:99
	ds_read2_b32 v[56:57], v15 offset0:132 offset1:165
	ds_read2_b32 v[58:59], v15 offset0:198 offset1:231
	ds_read2_b32 v[60:61], v15 offset0:8 offset1:41
	ds_read2_b32 v[62:63], v15 offset0:74 offset1:107
	ds_read2_b32 v[64:65], v15 offset0:140 offset1:173
	ds_read2_b32 v[66:67], v15 offset0:206 offset1:239
	ds_read2_b32 v[68:69], v15 offset0:16 offset1:49
	ds_read2_b32 v[70:71], v15 offset0:82 offset1:115
	ds_read2_b32 v[72:73], v15 offset0:148 offset1:181
	ds_read2_b32 v[74:75], v15 offset0:214 offset1:247
	ds_read2_b32 v[76:77], v15 offset0:24 offset1:57
	ds_read2_b32 v[78:79], v15 offset0:90 offset1:123
	ds_read2_b32 v[80:81], v15 offset0:156 offset1:189
	ds_read2_b32 v[82:83], v15 offset0:222 offset1:255
	s_add_u32 s95, s94, 0x1800
	s_lshr_b32 vcc_lo, s95, 7
	s_and_b32 vcc_hi, s95, 0x7f
	s_mul_i32 vcc_hi, vcc_hi, 0xac000
	s_lshl_b32 vcc_lo, vcc_lo, 7
	s_add_u32 s98, s66, 0x12d00000
	s_addc_u32 s99, s67, 0
	s_add_u32 s98, s98, vcc_hi
	s_addc_u32 s99, s99, 0
	s_add_u32 s98, s98, vcc_lo
	s_addc_u32 s99, s99, 0
	s_waitcnt lgkmcnt(0)
	v_cvt_pk_bf16_f32 v84, v52, v53
	v_cvt_pk_bf16_f32 v85, v54, v55
	v_cvt_pk_bf16_f32 v86, v56, v57
	v_cvt_pk_bf16_f32 v87, v58, v59
	v_cvt_pk_bf16_f32 v88, v60, v61
	v_cvt_pk_bf16_f32 v89, v62, v63
	v_cvt_pk_bf16_f32 v90, v64, v65
	v_cvt_pk_bf16_f32 v91, v66, v67
	v_cvt_pk_bf16_f32 v92, v68, v69
	v_cvt_pk_bf16_f32 v93, v70, v71
	v_cvt_pk_bf16_f32 v94, v72, v73
	v_cvt_pk_bf16_f32 v95, v74, v75
	v_cvt_pk_bf16_f32 v96, v76, v77
	v_cvt_pk_bf16_f32 v97, v78, v79
	v_cvt_pk_bf16_f32 v98, v80, v81
	v_cvt_pk_bf16_f32 v99, v82, v83
	global_store_dwordx4 v16, v[84:87], s[98:99]
	global_store_dwordx4 v17, v[88:91], s[98:99]
	global_store_dwordx4 v18, v[92:95], s[98:99]
	global_store_dwordx4 v19, v[96:99], s[98:99]
	s_waitcnt vmcnt(23)
	ds_write_b32 v14, v100 offset:0
	ds_write_b32 v14, v101 offset:4
	ds_write_b32 v14, v102 offset:8
	ds_write_b32 v14, v103 offset:12
	s_waitcnt vmcnt(22)
	ds_write_b32 v14, v104 offset:1056
	ds_write_b32 v14, v105 offset:1060
	ds_write_b32 v14, v106 offset:1064
	ds_write_b32 v14, v107 offset:1068
	s_waitcnt vmcnt(21)
	ds_write_b32 v14, v108 offset:2112
	ds_write_b32 v14, v109 offset:2116
	ds_write_b32 v14, v110 offset:2120
	ds_write_b32 v14, v111 offset:2124
	s_waitcnt vmcnt(20)
	ds_write_b32 v14, v112 offset:3168
	ds_write_b32 v14, v113 offset:3172
	ds_write_b32 v14, v114 offset:3176
	ds_write_b32 v14, v115 offset:3180
	s_waitcnt vmcnt(19)
	ds_write_b32 v14, v116 offset:4224
	ds_write_b32 v14, v117 offset:4228
	ds_write_b32 v14, v118 offset:4232
	ds_write_b32 v14, v119 offset:4236
	s_waitcnt vmcnt(18)
	ds_write_b32 v14, v120 offset:5280
	ds_write_b32 v14, v121 offset:5284
	ds_write_b32 v14, v122 offset:5288
	ds_write_b32 v14, v123 offset:5292
	s_waitcnt vmcnt(17)
	ds_write_b32 v14, v124 offset:6336
	ds_write_b32 v14, v125 offset:6340
	ds_write_b32 v14, v126 offset:6344
	ds_write_b32 v14, v127 offset:6348
	s_waitcnt vmcnt(16)
	ds_write_b32 v14, v128 offset:7392
	ds_write_b32 v14, v129 offset:7396
	ds_write_b32 v14, v130 offset:7400
	ds_write_b32 v14, v131 offset:7404
	s_add_u32 s95, s94, 0x2400
	s_lshr_b32 vcc_lo, s95, 7
	s_and_b32 vcc_hi, s95, 0x7f
	s_lshl_b32 vcc_lo, vcc_lo, 20
	s_lshl_b32 vcc_hi, vcc_hi, 7
	s_add_u32 s96, s100, vcc_lo
	s_addc_u32 s97, s101, 0
	s_add_u32 s96, s96, vcc_hi
	s_addc_u32 s97, s97, 0
	global_load_dwordx4 v[100:103], v6, s[96:97]
	global_load_dwordx4 v[104:107], v7, s[96:97]
	global_load_dwordx4 v[108:111], v8, s[96:97]
	global_load_dwordx4 v[112:115], v9, s[96:97]
	global_load_dwordx4 v[116:119], v10, s[96:97]
	global_load_dwordx4 v[120:123], v11, s[96:97]
	global_load_dwordx4 v[124:127], v12, s[96:97]
	global_load_dwordx4 v[128:131], v13, s[96:97]
	ds_read2_b32 v[52:53], v15 offset0:0 offset1:33
	ds_read2_b32 v[54:55], v15 offset0:66 offset1:99
	ds_read2_b32 v[56:57], v15 offset0:132 offset1:165
	ds_read2_b32 v[58:59], v15 offset0:198 offset1:231
	ds_read2_b32 v[60:61], v15 offset0:8 offset1:41
	ds_read2_b32 v[62:63], v15 offset0:74 offset1:107
	ds_read2_b32 v[64:65], v15 offset0:140 offset1:173
	ds_read2_b32 v[66:67], v15 offset0:206 offset1:239
	ds_read2_b32 v[68:69], v15 offset0:16 offset1:49
	ds_read2_b32 v[70:71], v15 offset0:82 offset1:115
	ds_read2_b32 v[72:73], v15 offset0:148 offset1:181
	ds_read2_b32 v[74:75], v15 offset0:214 offset1:247
	ds_read2_b32 v[76:77], v15 offset0:24 offset1:57
	ds_read2_b32 v[78:79], v15 offset0:90 offset1:123
	ds_read2_b32 v[80:81], v15 offset0:156 offset1:189
	ds_read2_b32 v[82:83], v15 offset0:222 offset1:255
	s_add_u32 s95, s94, 0x1c00
	s_lshr_b32 vcc_lo, s95, 7
	s_and_b32 vcc_hi, s95, 0x7f
	s_mul_i32 vcc_hi, vcc_hi, 0xac000
	s_lshl_b32 vcc_lo, vcc_lo, 7
	s_add_u32 s98, s66, 0x12d00000
	s_addc_u32 s99, s67, 0
	s_add_u32 s98, s98, vcc_hi
	s_addc_u32 s99, s99, 0
	s_add_u32 s98, s98, vcc_lo
	s_addc_u32 s99, s99, 0
	s_waitcnt lgkmcnt(0)
	v_cvt_pk_bf16_f32 v84, v52, v53
	v_cvt_pk_bf16_f32 v85, v54, v55
	v_cvt_pk_bf16_f32 v86, v56, v57
	v_cvt_pk_bf16_f32 v87, v58, v59
	v_cvt_pk_bf16_f32 v88, v60, v61
	v_cvt_pk_bf16_f32 v89, v62, v63
	v_cvt_pk_bf16_f32 v90, v64, v65
	v_cvt_pk_bf16_f32 v91, v66, v67
	v_cvt_pk_bf16_f32 v92, v68, v69
	v_cvt_pk_bf16_f32 v93, v70, v71
	v_cvt_pk_bf16_f32 v94, v72, v73
	v_cvt_pk_bf16_f32 v95, v74, v75
	v_cvt_pk_bf16_f32 v96, v76, v77
	v_cvt_pk_bf16_f32 v97, v78, v79
	v_cvt_pk_bf16_f32 v98, v80, v81
	v_cvt_pk_bf16_f32 v99, v82, v83
	global_store_dwordx4 v16, v[84:87], s[98:99]
	global_store_dwordx4 v17, v[88:91], s[98:99]
	global_store_dwordx4 v18, v[92:95], s[98:99]
	global_store_dwordx4 v19, v[96:99], s[98:99]
	s_waitcnt vmcnt(23)
	ds_write_b32 v14, v20 offset:0
	ds_write_b32 v14, v21 offset:4
	ds_write_b32 v14, v22 offset:8
	ds_write_b32 v14, v23 offset:12
	s_waitcnt vmcnt(22)
	ds_write_b32 v14, v24 offset:1056
	ds_write_b32 v14, v25 offset:1060
	ds_write_b32 v14, v26 offset:1064
	ds_write_b32 v14, v27 offset:1068
	s_waitcnt vmcnt(21)
	ds_write_b32 v14, v28 offset:2112
	ds_write_b32 v14, v29 offset:2116
	ds_write_b32 v14, v30 offset:2120
	ds_write_b32 v14, v31 offset:2124
	s_waitcnt vmcnt(20)
	ds_write_b32 v14, v32 offset:3168
	ds_write_b32 v14, v33 offset:3172
	ds_write_b32 v14, v34 offset:3176
	ds_write_b32 v14, v35 offset:3180
	s_waitcnt vmcnt(19)
	ds_write_b32 v14, v36 offset:4224
	ds_write_b32 v14, v37 offset:4228
	ds_write_b32 v14, v38 offset:4232
	ds_write_b32 v14, v39 offset:4236
	s_waitcnt vmcnt(18)
	ds_write_b32 v14, v40 offset:5280
	ds_write_b32 v14, v41 offset:5284
	ds_write_b32 v14, v42 offset:5288
	ds_write_b32 v14, v43 offset:5292
	s_waitcnt vmcnt(17)
	ds_write_b32 v14, v44 offset:6336
	ds_write_b32 v14, v45 offset:6340
	ds_write_b32 v14, v46 offset:6344
	ds_write_b32 v14, v47 offset:6348
	s_waitcnt vmcnt(16)
	ds_write_b32 v14, v48 offset:7392
	ds_write_b32 v14, v49 offset:7396
	ds_write_b32 v14, v50 offset:7400
	ds_write_b32 v14, v51 offset:7404
	s_add_u32 s95, s94, 0x2800
	s_lshr_b32 vcc_lo, s95, 7
	s_and_b32 vcc_hi, s95, 0x7f
	s_lshl_b32 vcc_lo, vcc_lo, 20
	s_lshl_b32 vcc_hi, vcc_hi, 7
	s_add_u32 s96, s100, vcc_lo
	s_addc_u32 s97, s101, 0
	s_add_u32 s96, s96, vcc_hi
	s_addc_u32 s97, s97, 0
	global_load_dwordx4 v[20:23], v6, s[96:97]
	global_load_dwordx4 v[24:27], v7, s[96:97]
	global_load_dwordx4 v[28:31], v8, s[96:97]
	global_load_dwordx4 v[32:35], v9, s[96:97]
	global_load_dwordx4 v[36:39], v10, s[96:97]
	global_load_dwordx4 v[40:43], v11, s[96:97]
	global_load_dwordx4 v[44:47], v12, s[96:97]
	global_load_dwordx4 v[48:51], v13, s[96:97]
	ds_read2_b32 v[52:53], v15 offset0:0 offset1:33
	ds_read2_b32 v[54:55], v15 offset0:66 offset1:99
	ds_read2_b32 v[56:57], v15 offset0:132 offset1:165
	ds_read2_b32 v[58:59], v15 offset0:198 offset1:231
	ds_read2_b32 v[60:61], v15 offset0:8 offset1:41
	ds_read2_b32 v[62:63], v15 offset0:74 offset1:107
	ds_read2_b32 v[64:65], v15 offset0:140 offset1:173
	ds_read2_b32 v[66:67], v15 offset0:206 offset1:239
	ds_read2_b32 v[68:69], v15 offset0:16 offset1:49
	ds_read2_b32 v[70:71], v15 offset0:82 offset1:115
	ds_read2_b32 v[72:73], v15 offset0:148 offset1:181
	ds_read2_b32 v[74:75], v15 offset0:214 offset1:247
	ds_read2_b32 v[76:77], v15 offset0:24 offset1:57
	ds_read2_b32 v[78:79], v15 offset0:90 offset1:123
	ds_read2_b32 v[80:81], v15 offset0:156 offset1:189
	ds_read2_b32 v[82:83], v15 offset0:222 offset1:255
	s_add_u32 s95, s94, 0x2000
	s_lshr_b32 vcc_lo, s95, 7
	s_and_b32 vcc_hi, s95, 0x7f
	s_mul_i32 vcc_hi, vcc_hi, 0xac000
	s_lshl_b32 vcc_lo, vcc_lo, 7
	s_add_u32 s98, s66, 0x12d00000
	s_addc_u32 s99, s67, 0
	s_add_u32 s98, s98, vcc_hi
	s_addc_u32 s99, s99, 0
	s_add_u32 s98, s98, vcc_lo
	s_addc_u32 s99, s99, 0
	s_waitcnt lgkmcnt(0)
	v_cvt_pk_bf16_f32 v84, v52, v53
	v_cvt_pk_bf16_f32 v85, v54, v55
	v_cvt_pk_bf16_f32 v86, v56, v57
	v_cvt_pk_bf16_f32 v87, v58, v59
	v_cvt_pk_bf16_f32 v88, v60, v61
	v_cvt_pk_bf16_f32 v89, v62, v63
	v_cvt_pk_bf16_f32 v90, v64, v65
	v_cvt_pk_bf16_f32 v91, v66, v67
	v_cvt_pk_bf16_f32 v92, v68, v69
	v_cvt_pk_bf16_f32 v93, v70, v71
	v_cvt_pk_bf16_f32 v94, v72, v73
	v_cvt_pk_bf16_f32 v95, v74, v75
	v_cvt_pk_bf16_f32 v96, v76, v77
	v_cvt_pk_bf16_f32 v97, v78, v79
	v_cvt_pk_bf16_f32 v98, v80, v81
	v_cvt_pk_bf16_f32 v99, v82, v83
	global_store_dwordx4 v16, v[84:87], s[98:99]
	global_store_dwordx4 v17, v[88:91], s[98:99]
	global_store_dwordx4 v18, v[92:95], s[98:99]
	global_store_dwordx4 v19, v[96:99], s[98:99]
	s_waitcnt vmcnt(23)
	ds_write_b32 v14, v100 offset:0
	ds_write_b32 v14, v101 offset:4
	ds_write_b32 v14, v102 offset:8
	ds_write_b32 v14, v103 offset:12
	s_waitcnt vmcnt(22)
	ds_write_b32 v14, v104 offset:1056
	ds_write_b32 v14, v105 offset:1060
	ds_write_b32 v14, v106 offset:1064
	ds_write_b32 v14, v107 offset:1068
	s_waitcnt vmcnt(21)
	ds_write_b32 v14, v108 offset:2112
	ds_write_b32 v14, v109 offset:2116
	ds_write_b32 v14, v110 offset:2120
	ds_write_b32 v14, v111 offset:2124
	s_waitcnt vmcnt(20)
	ds_write_b32 v14, v112 offset:3168
	ds_write_b32 v14, v113 offset:3172
	ds_write_b32 v14, v114 offset:3176
	ds_write_b32 v14, v115 offset:3180
	s_waitcnt vmcnt(19)
	ds_write_b32 v14, v116 offset:4224
	ds_write_b32 v14, v117 offset:4228
	ds_write_b32 v14, v118 offset:4232
	ds_write_b32 v14, v119 offset:4236
	s_waitcnt vmcnt(18)
	ds_write_b32 v14, v120 offset:5280
	ds_write_b32 v14, v121 offset:5284
	ds_write_b32 v14, v122 offset:5288
	ds_write_b32 v14, v123 offset:5292
	s_waitcnt vmcnt(17)
	ds_write_b32 v14, v124 offset:6336
	ds_write_b32 v14, v125 offset:6340
	ds_write_b32 v14, v126 offset:6344
	ds_write_b32 v14, v127 offset:6348
	s_waitcnt vmcnt(16)
	ds_write_b32 v14, v128 offset:7392
	ds_write_b32 v14, v129 offset:7396
	ds_write_b32 v14, v130 offset:7400
	ds_write_b32 v14, v131 offset:7404
	s_add_u32 s95, s94, 0x2c00
	s_lshr_b32 vcc_lo, s95, 7
	s_and_b32 vcc_hi, s95, 0x7f
	s_lshl_b32 vcc_lo, vcc_lo, 20
	s_lshl_b32 vcc_hi, vcc_hi, 7
	s_add_u32 s96, s100, vcc_lo
	s_addc_u32 s97, s101, 0
	s_add_u32 s96, s96, vcc_hi
	s_addc_u32 s97, s97, 0
	global_load_dwordx4 v[100:103], v6, s[96:97]
	global_load_dwordx4 v[104:107], v7, s[96:97]
	global_load_dwordx4 v[108:111], v8, s[96:97]
	global_load_dwordx4 v[112:115], v9, s[96:97]
	global_load_dwordx4 v[116:119], v10, s[96:97]
	global_load_dwordx4 v[120:123], v11, s[96:97]
	global_load_dwordx4 v[124:127], v12, s[96:97]
	global_load_dwordx4 v[128:131], v13, s[96:97]
	ds_read2_b32 v[52:53], v15 offset0:0 offset1:33
	ds_read2_b32 v[54:55], v15 offset0:66 offset1:99
	ds_read2_b32 v[56:57], v15 offset0:132 offset1:165
	ds_read2_b32 v[58:59], v15 offset0:198 offset1:231
	ds_read2_b32 v[60:61], v15 offset0:8 offset1:41
	ds_read2_b32 v[62:63], v15 offset0:74 offset1:107
	ds_read2_b32 v[64:65], v15 offset0:140 offset1:173
	ds_read2_b32 v[66:67], v15 offset0:206 offset1:239
	ds_read2_b32 v[68:69], v15 offset0:16 offset1:49
	ds_read2_b32 v[70:71], v15 offset0:82 offset1:115
	ds_read2_b32 v[72:73], v15 offset0:148 offset1:181
	ds_read2_b32 v[74:75], v15 offset0:214 offset1:247
	ds_read2_b32 v[76:77], v15 offset0:24 offset1:57
	ds_read2_b32 v[78:79], v15 offset0:90 offset1:123
	ds_read2_b32 v[80:81], v15 offset0:156 offset1:189
	ds_read2_b32 v[82:83], v15 offset0:222 offset1:255
	s_add_u32 s95, s94, 0x2400
	s_lshr_b32 vcc_lo, s95, 7
	s_and_b32 vcc_hi, s95, 0x7f
	s_mul_i32 vcc_hi, vcc_hi, 0xac000
	s_lshl_b32 vcc_lo, vcc_lo, 7
	s_add_u32 s98, s66, 0x12d00000
	s_addc_u32 s99, s67, 0
	s_add_u32 s98, s98, vcc_hi
	s_addc_u32 s99, s99, 0
	s_add_u32 s98, s98, vcc_lo
	s_addc_u32 s99, s99, 0
	s_waitcnt lgkmcnt(0)
	v_cvt_pk_bf16_f32 v84, v52, v53
	v_cvt_pk_bf16_f32 v85, v54, v55
	v_cvt_pk_bf16_f32 v86, v56, v57
	v_cvt_pk_bf16_f32 v87, v58, v59
	v_cvt_pk_bf16_f32 v88, v60, v61
	v_cvt_pk_bf16_f32 v89, v62, v63
	v_cvt_pk_bf16_f32 v90, v64, v65
	v_cvt_pk_bf16_f32 v91, v66, v67
	v_cvt_pk_bf16_f32 v92, v68, v69
	v_cvt_pk_bf16_f32 v93, v70, v71
	v_cvt_pk_bf16_f32 v94, v72, v73
	v_cvt_pk_bf16_f32 v95, v74, v75
	v_cvt_pk_bf16_f32 v96, v76, v77
	v_cvt_pk_bf16_f32 v97, v78, v79
	v_cvt_pk_bf16_f32 v98, v80, v81
	v_cvt_pk_bf16_f32 v99, v82, v83
	global_store_dwordx4 v16, v[84:87], s[98:99]
	global_store_dwordx4 v17, v[88:91], s[98:99]
	global_store_dwordx4 v18, v[92:95], s[98:99]
	global_store_dwordx4 v19, v[96:99], s[98:99]
	s_waitcnt vmcnt(23)
	ds_write_b32 v14, v20 offset:0
	ds_write_b32 v14, v21 offset:4
	ds_write_b32 v14, v22 offset:8
	ds_write_b32 v14, v23 offset:12
	s_waitcnt vmcnt(22)
	ds_write_b32 v14, v24 offset:1056
	ds_write_b32 v14, v25 offset:1060
	ds_write_b32 v14, v26 offset:1064
	ds_write_b32 v14, v27 offset:1068
	s_waitcnt vmcnt(21)
	ds_write_b32 v14, v28 offset:2112
	ds_write_b32 v14, v29 offset:2116
	ds_write_b32 v14, v30 offset:2120
	ds_write_b32 v14, v31 offset:2124
	s_waitcnt vmcnt(20)
	ds_write_b32 v14, v32 offset:3168
	ds_write_b32 v14, v33 offset:3172
	ds_write_b32 v14, v34 offset:3176
	ds_write_b32 v14, v35 offset:3180
	s_waitcnt vmcnt(19)
	ds_write_b32 v14, v36 offset:4224
	ds_write_b32 v14, v37 offset:4228
	ds_write_b32 v14, v38 offset:4232
	ds_write_b32 v14, v39 offset:4236
	s_waitcnt vmcnt(18)
	ds_write_b32 v14, v40 offset:5280
	ds_write_b32 v14, v41 offset:5284
	ds_write_b32 v14, v42 offset:5288
	ds_write_b32 v14, v43 offset:5292
	s_waitcnt vmcnt(17)
	ds_write_b32 v14, v44 offset:6336
	ds_write_b32 v14, v45 offset:6340
	ds_write_b32 v14, v46 offset:6344
	ds_write_b32 v14, v47 offset:6348
	s_waitcnt vmcnt(16)
	ds_write_b32 v14, v48 offset:7392
	ds_write_b32 v14, v49 offset:7396
	ds_write_b32 v14, v50 offset:7400
	ds_write_b32 v14, v51 offset:7404
	s_add_u32 s95, s94, 0x3000
	s_lshr_b32 vcc_lo, s95, 7
	s_and_b32 vcc_hi, s95, 0x7f
	s_lshl_b32 vcc_lo, vcc_lo, 20
	s_lshl_b32 vcc_hi, vcc_hi, 7
	s_add_u32 s96, s100, vcc_lo
	s_addc_u32 s97, s101, 0
	s_add_u32 s96, s96, vcc_hi
	s_addc_u32 s97, s97, 0
	global_load_dwordx4 v[20:23], v6, s[96:97]
	global_load_dwordx4 v[24:27], v7, s[96:97]
	global_load_dwordx4 v[28:31], v8, s[96:97]
	global_load_dwordx4 v[32:35], v9, s[96:97]
	global_load_dwordx4 v[36:39], v10, s[96:97]
	global_load_dwordx4 v[40:43], v11, s[96:97]
	global_load_dwordx4 v[44:47], v12, s[96:97]
	global_load_dwordx4 v[48:51], v13, s[96:97]
	ds_read2_b32 v[52:53], v15 offset0:0 offset1:33
	ds_read2_b32 v[54:55], v15 offset0:66 offset1:99
	ds_read2_b32 v[56:57], v15 offset0:132 offset1:165
	ds_read2_b32 v[58:59], v15 offset0:198 offset1:231
	ds_read2_b32 v[60:61], v15 offset0:8 offset1:41
	ds_read2_b32 v[62:63], v15 offset0:74 offset1:107
	ds_read2_b32 v[64:65], v15 offset0:140 offset1:173
	ds_read2_b32 v[66:67], v15 offset0:206 offset1:239
	ds_read2_b32 v[68:69], v15 offset0:16 offset1:49
	ds_read2_b32 v[70:71], v15 offset0:82 offset1:115
	ds_read2_b32 v[72:73], v15 offset0:148 offset1:181
	ds_read2_b32 v[74:75], v15 offset0:214 offset1:247
	ds_read2_b32 v[76:77], v15 offset0:24 offset1:57
	ds_read2_b32 v[78:79], v15 offset0:90 offset1:123
	ds_read2_b32 v[80:81], v15 offset0:156 offset1:189
	ds_read2_b32 v[82:83], v15 offset0:222 offset1:255
	s_add_u32 s95, s94, 0x2800
	s_lshr_b32 vcc_lo, s95, 7
	s_and_b32 vcc_hi, s95, 0x7f
	s_mul_i32 vcc_hi, vcc_hi, 0xac000
	s_lshl_b32 vcc_lo, vcc_lo, 7
	s_add_u32 s98, s66, 0x12d00000
	s_addc_u32 s99, s67, 0
	s_add_u32 s98, s98, vcc_hi
	s_addc_u32 s99, s99, 0
	s_add_u32 s98, s98, vcc_lo
	s_addc_u32 s99, s99, 0
	s_waitcnt lgkmcnt(0)
	v_cvt_pk_bf16_f32 v84, v52, v53
	v_cvt_pk_bf16_f32 v85, v54, v55
	v_cvt_pk_bf16_f32 v86, v56, v57
	v_cvt_pk_bf16_f32 v87, v58, v59
	v_cvt_pk_bf16_f32 v88, v60, v61
	v_cvt_pk_bf16_f32 v89, v62, v63
	v_cvt_pk_bf16_f32 v90, v64, v65
	v_cvt_pk_bf16_f32 v91, v66, v67
	v_cvt_pk_bf16_f32 v92, v68, v69
	v_cvt_pk_bf16_f32 v93, v70, v71
	v_cvt_pk_bf16_f32 v94, v72, v73
	v_cvt_pk_bf16_f32 v95, v74, v75
	v_cvt_pk_bf16_f32 v96, v76, v77
	v_cvt_pk_bf16_f32 v97, v78, v79
	v_cvt_pk_bf16_f32 v98, v80, v81
	v_cvt_pk_bf16_f32 v99, v82, v83
	global_store_dwordx4 v16, v[84:87], s[98:99]
	global_store_dwordx4 v17, v[88:91], s[98:99]
	global_store_dwordx4 v18, v[92:95], s[98:99]
	global_store_dwordx4 v19, v[96:99], s[98:99]
	s_waitcnt vmcnt(23)
	ds_write_b32 v14, v100 offset:0
	ds_write_b32 v14, v101 offset:4
	ds_write_b32 v14, v102 offset:8
	ds_write_b32 v14, v103 offset:12
	s_waitcnt vmcnt(22)
	ds_write_b32 v14, v104 offset:1056
	ds_write_b32 v14, v105 offset:1060
	ds_write_b32 v14, v106 offset:1064
	ds_write_b32 v14, v107 offset:1068
	s_waitcnt vmcnt(21)
	ds_write_b32 v14, v108 offset:2112
	ds_write_b32 v14, v109 offset:2116
	ds_write_b32 v14, v110 offset:2120
	ds_write_b32 v14, v111 offset:2124
	s_waitcnt vmcnt(20)
	ds_write_b32 v14, v112 offset:3168
	ds_write_b32 v14, v113 offset:3172
	ds_write_b32 v14, v114 offset:3176
	ds_write_b32 v14, v115 offset:3180
	s_waitcnt vmcnt(19)
	ds_write_b32 v14, v116 offset:4224
	ds_write_b32 v14, v117 offset:4228
	ds_write_b32 v14, v118 offset:4232
	ds_write_b32 v14, v119 offset:4236
	s_waitcnt vmcnt(18)
	ds_write_b32 v14, v120 offset:5280
	ds_write_b32 v14, v121 offset:5284
	ds_write_b32 v14, v122 offset:5288
	ds_write_b32 v14, v123 offset:5292
	s_waitcnt vmcnt(17)
	ds_write_b32 v14, v124 offset:6336
	ds_write_b32 v14, v125 offset:6340
	ds_write_b32 v14, v126 offset:6344
	ds_write_b32 v14, v127 offset:6348
	s_waitcnt vmcnt(16)
	ds_write_b32 v14, v128 offset:7392
	ds_write_b32 v14, v129 offset:7396
	ds_write_b32 v14, v130 offset:7400
	ds_write_b32 v14, v131 offset:7404
	s_add_u32 s95, s94, 0x3400
	s_lshr_b32 vcc_lo, s95, 7
	s_and_b32 vcc_hi, s95, 0x7f
	s_lshl_b32 vcc_lo, vcc_lo, 20
	s_lshl_b32 vcc_hi, vcc_hi, 7
	s_add_u32 s96, s100, vcc_lo
	s_addc_u32 s97, s101, 0
	s_add_u32 s96, s96, vcc_hi
	s_addc_u32 s97, s97, 0
	global_load_dwordx4 v[100:103], v6, s[96:97]
	global_load_dwordx4 v[104:107], v7, s[96:97]
	global_load_dwordx4 v[108:111], v8, s[96:97]
	global_load_dwordx4 v[112:115], v9, s[96:97]
	global_load_dwordx4 v[116:119], v10, s[96:97]
	global_load_dwordx4 v[120:123], v11, s[96:97]
	global_load_dwordx4 v[124:127], v12, s[96:97]
	global_load_dwordx4 v[128:131], v13, s[96:97]
	ds_read2_b32 v[52:53], v15 offset0:0 offset1:33
	ds_read2_b32 v[54:55], v15 offset0:66 offset1:99
	ds_read2_b32 v[56:57], v15 offset0:132 offset1:165
	ds_read2_b32 v[58:59], v15 offset0:198 offset1:231
	ds_read2_b32 v[60:61], v15 offset0:8 offset1:41
	ds_read2_b32 v[62:63], v15 offset0:74 offset1:107
	ds_read2_b32 v[64:65], v15 offset0:140 offset1:173
	ds_read2_b32 v[66:67], v15 offset0:206 offset1:239
	ds_read2_b32 v[68:69], v15 offset0:16 offset1:49
	ds_read2_b32 v[70:71], v15 offset0:82 offset1:115
	ds_read2_b32 v[72:73], v15 offset0:148 offset1:181
	ds_read2_b32 v[74:75], v15 offset0:214 offset1:247
	ds_read2_b32 v[76:77], v15 offset0:24 offset1:57
	ds_read2_b32 v[78:79], v15 offset0:90 offset1:123
	ds_read2_b32 v[80:81], v15 offset0:156 offset1:189
	ds_read2_b32 v[82:83], v15 offset0:222 offset1:255
	s_add_u32 s95, s94, 0x2c00
	s_lshr_b32 vcc_lo, s95, 7
	s_and_b32 vcc_hi, s95, 0x7f
	s_mul_i32 vcc_hi, vcc_hi, 0xac000
	s_lshl_b32 vcc_lo, vcc_lo, 7
	s_add_u32 s98, s66, 0x12d00000
	s_addc_u32 s99, s67, 0
	s_add_u32 s98, s98, vcc_hi
	s_addc_u32 s99, s99, 0
	s_add_u32 s98, s98, vcc_lo
	s_addc_u32 s99, s99, 0
	s_waitcnt lgkmcnt(0)
	v_cvt_pk_bf16_f32 v84, v52, v53
	v_cvt_pk_bf16_f32 v85, v54, v55
	v_cvt_pk_bf16_f32 v86, v56, v57
	v_cvt_pk_bf16_f32 v87, v58, v59
	v_cvt_pk_bf16_f32 v88, v60, v61
	v_cvt_pk_bf16_f32 v89, v62, v63
	v_cvt_pk_bf16_f32 v90, v64, v65
	v_cvt_pk_bf16_f32 v91, v66, v67
	v_cvt_pk_bf16_f32 v92, v68, v69
	v_cvt_pk_bf16_f32 v93, v70, v71
	v_cvt_pk_bf16_f32 v94, v72, v73
	v_cvt_pk_bf16_f32 v95, v74, v75
	v_cvt_pk_bf16_f32 v96, v76, v77
	v_cvt_pk_bf16_f32 v97, v78, v79
	v_cvt_pk_bf16_f32 v98, v80, v81
	v_cvt_pk_bf16_f32 v99, v82, v83
	global_store_dwordx4 v16, v[84:87], s[98:99]
	global_store_dwordx4 v17, v[88:91], s[98:99]
	global_store_dwordx4 v18, v[92:95], s[98:99]
	global_store_dwordx4 v19, v[96:99], s[98:99]
	s_waitcnt vmcnt(23)
	ds_write_b32 v14, v20 offset:0
	ds_write_b32 v14, v21 offset:4
	ds_write_b32 v14, v22 offset:8
	ds_write_b32 v14, v23 offset:12
	s_waitcnt vmcnt(22)
	ds_write_b32 v14, v24 offset:1056
	ds_write_b32 v14, v25 offset:1060
	ds_write_b32 v14, v26 offset:1064
	ds_write_b32 v14, v27 offset:1068
	s_waitcnt vmcnt(21)
	ds_write_b32 v14, v28 offset:2112
	ds_write_b32 v14, v29 offset:2116
	ds_write_b32 v14, v30 offset:2120
	ds_write_b32 v14, v31 offset:2124
	s_waitcnt vmcnt(20)
	ds_write_b32 v14, v32 offset:3168
	ds_write_b32 v14, v33 offset:3172
	ds_write_b32 v14, v34 offset:3176
	ds_write_b32 v14, v35 offset:3180
	s_waitcnt vmcnt(19)
	ds_write_b32 v14, v36 offset:4224
	ds_write_b32 v14, v37 offset:4228
	ds_write_b32 v14, v38 offset:4232
	ds_write_b32 v14, v39 offset:4236
	s_waitcnt vmcnt(18)
	ds_write_b32 v14, v40 offset:5280
	ds_write_b32 v14, v41 offset:5284
	ds_write_b32 v14, v42 offset:5288
	ds_write_b32 v14, v43 offset:5292
	s_waitcnt vmcnt(17)
	ds_write_b32 v14, v44 offset:6336
	ds_write_b32 v14, v45 offset:6340
	ds_write_b32 v14, v46 offset:6344
	ds_write_b32 v14, v47 offset:6348
	s_waitcnt vmcnt(16)
	ds_write_b32 v14, v48 offset:7392
	ds_write_b32 v14, v49 offset:7396
	ds_write_b32 v14, v50 offset:7400
	ds_write_b32 v14, v51 offset:7404
	s_add_u32 s95, s94, 0x3800
	s_lshr_b32 vcc_lo, s95, 7
	s_and_b32 vcc_hi, s95, 0x7f
	s_lshl_b32 vcc_lo, vcc_lo, 20
	s_lshl_b32 vcc_hi, vcc_hi, 7
	s_add_u32 s96, s100, vcc_lo
	s_addc_u32 s97, s101, 0
	s_add_u32 s96, s96, vcc_hi
	s_addc_u32 s97, s97, 0
	global_load_dwordx4 v[20:23], v6, s[96:97]
	global_load_dwordx4 v[24:27], v7, s[96:97]
	global_load_dwordx4 v[28:31], v8, s[96:97]
	global_load_dwordx4 v[32:35], v9, s[96:97]
	global_load_dwordx4 v[36:39], v10, s[96:97]
	global_load_dwordx4 v[40:43], v11, s[96:97]
	global_load_dwordx4 v[44:47], v12, s[96:97]
	global_load_dwordx4 v[48:51], v13, s[96:97]
	ds_read2_b32 v[52:53], v15 offset0:0 offset1:33
	ds_read2_b32 v[54:55], v15 offset0:66 offset1:99
	ds_read2_b32 v[56:57], v15 offset0:132 offset1:165
	ds_read2_b32 v[58:59], v15 offset0:198 offset1:231
	ds_read2_b32 v[60:61], v15 offset0:8 offset1:41
	ds_read2_b32 v[62:63], v15 offset0:74 offset1:107
	ds_read2_b32 v[64:65], v15 offset0:140 offset1:173
	ds_read2_b32 v[66:67], v15 offset0:206 offset1:239
	ds_read2_b32 v[68:69], v15 offset0:16 offset1:49
	ds_read2_b32 v[70:71], v15 offset0:82 offset1:115
	ds_read2_b32 v[72:73], v15 offset0:148 offset1:181
	ds_read2_b32 v[74:75], v15 offset0:214 offset1:247
	ds_read2_b32 v[76:77], v15 offset0:24 offset1:57
	ds_read2_b32 v[78:79], v15 offset0:90 offset1:123
	ds_read2_b32 v[80:81], v15 offset0:156 offset1:189
	ds_read2_b32 v[82:83], v15 offset0:222 offset1:255
	s_add_u32 s95, s94, 0x3000
	s_lshr_b32 vcc_lo, s95, 7
	s_and_b32 vcc_hi, s95, 0x7f
	s_mul_i32 vcc_hi, vcc_hi, 0xac000
	s_lshl_b32 vcc_lo, vcc_lo, 7
	s_add_u32 s98, s66, 0x12d00000
	s_addc_u32 s99, s67, 0
	s_add_u32 s98, s98, vcc_hi
	s_addc_u32 s99, s99, 0
	s_add_u32 s98, s98, vcc_lo
	s_addc_u32 s99, s99, 0
	s_waitcnt lgkmcnt(0)
	v_cvt_pk_bf16_f32 v84, v52, v53
	v_cvt_pk_bf16_f32 v85, v54, v55
	v_cvt_pk_bf16_f32 v86, v56, v57
	v_cvt_pk_bf16_f32 v87, v58, v59
	v_cvt_pk_bf16_f32 v88, v60, v61
	v_cvt_pk_bf16_f32 v89, v62, v63
	v_cvt_pk_bf16_f32 v90, v64, v65
	v_cvt_pk_bf16_f32 v91, v66, v67
	v_cvt_pk_bf16_f32 v92, v68, v69
	v_cvt_pk_bf16_f32 v93, v70, v71
	v_cvt_pk_bf16_f32 v94, v72, v73
	v_cvt_pk_bf16_f32 v95, v74, v75
	v_cvt_pk_bf16_f32 v96, v76, v77
	v_cvt_pk_bf16_f32 v97, v78, v79
	v_cvt_pk_bf16_f32 v98, v80, v81
	v_cvt_pk_bf16_f32 v99, v82, v83
	global_store_dwordx4 v16, v[84:87], s[98:99]
	global_store_dwordx4 v17, v[88:91], s[98:99]
	global_store_dwordx4 v18, v[92:95], s[98:99]
	global_store_dwordx4 v19, v[96:99], s[98:99]
	s_waitcnt vmcnt(23)
	ds_write_b32 v14, v100 offset:0
	ds_write_b32 v14, v101 offset:4
	ds_write_b32 v14, v102 offset:8
	ds_write_b32 v14, v103 offset:12
	s_waitcnt vmcnt(22)
	ds_write_b32 v14, v104 offset:1056
	ds_write_b32 v14, v105 offset:1060
	ds_write_b32 v14, v106 offset:1064
	ds_write_b32 v14, v107 offset:1068
	s_waitcnt vmcnt(21)
	ds_write_b32 v14, v108 offset:2112
	ds_write_b32 v14, v109 offset:2116
	ds_write_b32 v14, v110 offset:2120
	ds_write_b32 v14, v111 offset:2124
	s_waitcnt vmcnt(20)
	ds_write_b32 v14, v112 offset:3168
	ds_write_b32 v14, v113 offset:3172
	ds_write_b32 v14, v114 offset:3176
	ds_write_b32 v14, v115 offset:3180
	s_waitcnt vmcnt(19)
	ds_write_b32 v14, v116 offset:4224
	ds_write_b32 v14, v117 offset:4228
	ds_write_b32 v14, v118 offset:4232
	ds_write_b32 v14, v119 offset:4236
	s_waitcnt vmcnt(18)
	ds_write_b32 v14, v120 offset:5280
	ds_write_b32 v14, v121 offset:5284
	ds_write_b32 v14, v122 offset:5288
	ds_write_b32 v14, v123 offset:5292
	s_waitcnt vmcnt(17)
	ds_write_b32 v14, v124 offset:6336
	ds_write_b32 v14, v125 offset:6340
	ds_write_b32 v14, v126 offset:6344
	ds_write_b32 v14, v127 offset:6348
	s_waitcnt vmcnt(16)
	ds_write_b32 v14, v128 offset:7392
	ds_write_b32 v14, v129 offset:7396
	ds_write_b32 v14, v130 offset:7400
	ds_write_b32 v14, v131 offset:7404
	s_add_u32 s95, s94, 0x3c00
	s_lshr_b32 vcc_lo, s95, 7
	s_and_b32 vcc_hi, s95, 0x7f
	s_lshl_b32 vcc_lo, vcc_lo, 20
	s_lshl_b32 vcc_hi, vcc_hi, 7
	s_add_u32 s96, s100, vcc_lo
	s_addc_u32 s97, s101, 0
	s_add_u32 s96, s96, vcc_hi
	s_addc_u32 s97, s97, 0
	global_load_dwordx4 v[100:103], v6, s[96:97]
	global_load_dwordx4 v[104:107], v7, s[96:97]
	global_load_dwordx4 v[108:111], v8, s[96:97]
	global_load_dwordx4 v[112:115], v9, s[96:97]
	global_load_dwordx4 v[116:119], v10, s[96:97]
	global_load_dwordx4 v[120:123], v11, s[96:97]
	global_load_dwordx4 v[124:127], v12, s[96:97]
	global_load_dwordx4 v[128:131], v13, s[96:97]
	ds_read2_b32 v[52:53], v15 offset0:0 offset1:33
	ds_read2_b32 v[54:55], v15 offset0:66 offset1:99
	ds_read2_b32 v[56:57], v15 offset0:132 offset1:165
	ds_read2_b32 v[58:59], v15 offset0:198 offset1:231
	ds_read2_b32 v[60:61], v15 offset0:8 offset1:41
	ds_read2_b32 v[62:63], v15 offset0:74 offset1:107
	ds_read2_b32 v[64:65], v15 offset0:140 offset1:173
	ds_read2_b32 v[66:67], v15 offset0:206 offset1:239
	ds_read2_b32 v[68:69], v15 offset0:16 offset1:49
	ds_read2_b32 v[70:71], v15 offset0:82 offset1:115
	ds_read2_b32 v[72:73], v15 offset0:148 offset1:181
	ds_read2_b32 v[74:75], v15 offset0:214 offset1:247
	ds_read2_b32 v[76:77], v15 offset0:24 offset1:57
	ds_read2_b32 v[78:79], v15 offset0:90 offset1:123
	ds_read2_b32 v[80:81], v15 offset0:156 offset1:189
	ds_read2_b32 v[82:83], v15 offset0:222 offset1:255
	s_add_u32 s95, s94, 0x3400
	s_lshr_b32 vcc_lo, s95, 7
	s_and_b32 vcc_hi, s95, 0x7f
	s_mul_i32 vcc_hi, vcc_hi, 0xac000
	s_lshl_b32 vcc_lo, vcc_lo, 7
	s_add_u32 s98, s66, 0x12d00000
	s_addc_u32 s99, s67, 0
	s_add_u32 s98, s98, vcc_hi
	s_addc_u32 s99, s99, 0
	s_add_u32 s98, s98, vcc_lo
	s_addc_u32 s99, s99, 0
	s_waitcnt lgkmcnt(0)
	v_cvt_pk_bf16_f32 v84, v52, v53
	v_cvt_pk_bf16_f32 v85, v54, v55
	v_cvt_pk_bf16_f32 v86, v56, v57
	v_cvt_pk_bf16_f32 v87, v58, v59
	v_cvt_pk_bf16_f32 v88, v60, v61
	v_cvt_pk_bf16_f32 v89, v62, v63
	v_cvt_pk_bf16_f32 v90, v64, v65
	v_cvt_pk_bf16_f32 v91, v66, v67
	v_cvt_pk_bf16_f32 v92, v68, v69
	v_cvt_pk_bf16_f32 v93, v70, v71
	v_cvt_pk_bf16_f32 v94, v72, v73
	v_cvt_pk_bf16_f32 v95, v74, v75
	v_cvt_pk_bf16_f32 v96, v76, v77
	v_cvt_pk_bf16_f32 v97, v78, v79
	v_cvt_pk_bf16_f32 v98, v80, v81
	v_cvt_pk_bf16_f32 v99, v82, v83
	global_store_dwordx4 v16, v[84:87], s[98:99]
	global_store_dwordx4 v17, v[88:91], s[98:99]
	global_store_dwordx4 v18, v[92:95], s[98:99]
	global_store_dwordx4 v19, v[96:99], s[98:99]
	s_waitcnt vmcnt(23)
	ds_write_b32 v14, v20 offset:0
	ds_write_b32 v14, v21 offset:4
	ds_write_b32 v14, v22 offset:8
	ds_write_b32 v14, v23 offset:12
	s_waitcnt vmcnt(22)
	ds_write_b32 v14, v24 offset:1056
	ds_write_b32 v14, v25 offset:1060
	ds_write_b32 v14, v26 offset:1064
	ds_write_b32 v14, v27 offset:1068
	s_waitcnt vmcnt(21)
	ds_write_b32 v14, v28 offset:2112
	ds_write_b32 v14, v29 offset:2116
	ds_write_b32 v14, v30 offset:2120
	ds_write_b32 v14, v31 offset:2124
	s_waitcnt vmcnt(20)
	ds_write_b32 v14, v32 offset:3168
	ds_write_b32 v14, v33 offset:3172
	ds_write_b32 v14, v34 offset:3176
	ds_write_b32 v14, v35 offset:3180
	s_waitcnt vmcnt(19)
	ds_write_b32 v14, v36 offset:4224
	ds_write_b32 v14, v37 offset:4228
	ds_write_b32 v14, v38 offset:4232
	ds_write_b32 v14, v39 offset:4236
	s_waitcnt vmcnt(18)
	ds_write_b32 v14, v40 offset:5280
	ds_write_b32 v14, v41 offset:5284
	ds_write_b32 v14, v42 offset:5288
	ds_write_b32 v14, v43 offset:5292
	s_waitcnt vmcnt(17)
	ds_write_b32 v14, v44 offset:6336
	ds_write_b32 v14, v45 offset:6340
	ds_write_b32 v14, v46 offset:6344
	ds_write_b32 v14, v47 offset:6348
	s_waitcnt vmcnt(16)
	ds_write_b32 v14, v48 offset:7392
	ds_write_b32 v14, v49 offset:7396
	ds_write_b32 v14, v50 offset:7400
	ds_write_b32 v14, v51 offset:7404
	s_add_u32 s95, s94, 0x4000
	s_lshr_b32 vcc_lo, s95, 7
	s_and_b32 vcc_hi, s95, 0x7f
	s_lshl_b32 vcc_lo, vcc_lo, 20
	s_lshl_b32 vcc_hi, vcc_hi, 7
	s_add_u32 s96, s100, vcc_lo
	s_addc_u32 s97, s101, 0
	s_add_u32 s96, s96, vcc_hi
	s_addc_u32 s97, s97, 0
	global_load_dwordx4 v[20:23], v6, s[96:97]
	global_load_dwordx4 v[24:27], v7, s[96:97]
	global_load_dwordx4 v[28:31], v8, s[96:97]
	global_load_dwordx4 v[32:35], v9, s[96:97]
	global_load_dwordx4 v[36:39], v10, s[96:97]
	global_load_dwordx4 v[40:43], v11, s[96:97]
	global_load_dwordx4 v[44:47], v12, s[96:97]
	global_load_dwordx4 v[48:51], v13, s[96:97]
	ds_read2_b32 v[52:53], v15 offset0:0 offset1:33
	ds_read2_b32 v[54:55], v15 offset0:66 offset1:99
	ds_read2_b32 v[56:57], v15 offset0:132 offset1:165
	ds_read2_b32 v[58:59], v15 offset0:198 offset1:231
	ds_read2_b32 v[60:61], v15 offset0:8 offset1:41
	ds_read2_b32 v[62:63], v15 offset0:74 offset1:107
	ds_read2_b32 v[64:65], v15 offset0:140 offset1:173
	ds_read2_b32 v[66:67], v15 offset0:206 offset1:239
	ds_read2_b32 v[68:69], v15 offset0:16 offset1:49
	ds_read2_b32 v[70:71], v15 offset0:82 offset1:115
	ds_read2_b32 v[72:73], v15 offset0:148 offset1:181
	ds_read2_b32 v[74:75], v15 offset0:214 offset1:247
	ds_read2_b32 v[76:77], v15 offset0:24 offset1:57
	ds_read2_b32 v[78:79], v15 offset0:90 offset1:123
	ds_read2_b32 v[80:81], v15 offset0:156 offset1:189
	ds_read2_b32 v[82:83], v15 offset0:222 offset1:255
	s_add_u32 s95, s94, 0x3800
	s_lshr_b32 vcc_lo, s95, 7
	s_and_b32 vcc_hi, s95, 0x7f
	s_mul_i32 vcc_hi, vcc_hi, 0xac000
	s_lshl_b32 vcc_lo, vcc_lo, 7
	s_add_u32 s98, s66, 0x12d00000
	s_addc_u32 s99, s67, 0
	s_add_u32 s98, s98, vcc_hi
	s_addc_u32 s99, s99, 0
	s_add_u32 s98, s98, vcc_lo
	s_addc_u32 s99, s99, 0
	s_waitcnt lgkmcnt(0)
	v_cvt_pk_bf16_f32 v84, v52, v53
	v_cvt_pk_bf16_f32 v85, v54, v55
	v_cvt_pk_bf16_f32 v86, v56, v57
	v_cvt_pk_bf16_f32 v87, v58, v59
	v_cvt_pk_bf16_f32 v88, v60, v61
	v_cvt_pk_bf16_f32 v89, v62, v63
	v_cvt_pk_bf16_f32 v90, v64, v65
	v_cvt_pk_bf16_f32 v91, v66, v67
	v_cvt_pk_bf16_f32 v92, v68, v69
	v_cvt_pk_bf16_f32 v93, v70, v71
	v_cvt_pk_bf16_f32 v94, v72, v73
	v_cvt_pk_bf16_f32 v95, v74, v75
	v_cvt_pk_bf16_f32 v96, v76, v77
	v_cvt_pk_bf16_f32 v97, v78, v79
	v_cvt_pk_bf16_f32 v98, v80, v81
	v_cvt_pk_bf16_f32 v99, v82, v83
	global_store_dwordx4 v16, v[84:87], s[98:99]
	global_store_dwordx4 v17, v[88:91], s[98:99]
	global_store_dwordx4 v18, v[92:95], s[98:99]
	global_store_dwordx4 v19, v[96:99], s[98:99]
	s_waitcnt vmcnt(23)
	ds_write_b32 v14, v100 offset:0
	ds_write_b32 v14, v101 offset:4
	ds_write_b32 v14, v102 offset:8
	ds_write_b32 v14, v103 offset:12
	s_waitcnt vmcnt(22)
	ds_write_b32 v14, v104 offset:1056
	ds_write_b32 v14, v105 offset:1060
	ds_write_b32 v14, v106 offset:1064
	ds_write_b32 v14, v107 offset:1068
	s_waitcnt vmcnt(21)
	ds_write_b32 v14, v108 offset:2112
	ds_write_b32 v14, v109 offset:2116
	ds_write_b32 v14, v110 offset:2120
	ds_write_b32 v14, v111 offset:2124
	s_waitcnt vmcnt(20)
	ds_write_b32 v14, v112 offset:3168
	ds_write_b32 v14, v113 offset:3172
	ds_write_b32 v14, v114 offset:3176
	ds_write_b32 v14, v115 offset:3180
	s_waitcnt vmcnt(19)
	ds_write_b32 v14, v116 offset:4224
	ds_write_b32 v14, v117 offset:4228
	ds_write_b32 v14, v118 offset:4232
	ds_write_b32 v14, v119 offset:4236
	s_waitcnt vmcnt(18)
	ds_write_b32 v14, v120 offset:5280
	ds_write_b32 v14, v121 offset:5284
	ds_write_b32 v14, v122 offset:5288
	ds_write_b32 v14, v123 offset:5292
	s_waitcnt vmcnt(17)
	ds_write_b32 v14, v124 offset:6336
	ds_write_b32 v14, v125 offset:6340
	ds_write_b32 v14, v126 offset:6344
	ds_write_b32 v14, v127 offset:6348
	s_waitcnt vmcnt(16)
	ds_write_b32 v14, v128 offset:7392
	ds_write_b32 v14, v129 offset:7396
	ds_write_b32 v14, v130 offset:7400
	ds_write_b32 v14, v131 offset:7404
	s_add_u32 s95, s94, 0x4400
	s_lshr_b32 vcc_lo, s95, 7
	s_and_b32 vcc_hi, s95, 0x7f
	s_lshl_b32 vcc_lo, vcc_lo, 20
	s_lshl_b32 vcc_hi, vcc_hi, 7
	s_add_u32 s96, s100, vcc_lo
	s_addc_u32 s97, s101, 0
	s_add_u32 s96, s96, vcc_hi
	s_addc_u32 s97, s97, 0
	global_load_dwordx4 v[100:103], v6, s[96:97]
	global_load_dwordx4 v[104:107], v7, s[96:97]
	global_load_dwordx4 v[108:111], v8, s[96:97]
	global_load_dwordx4 v[112:115], v9, s[96:97]
	global_load_dwordx4 v[116:119], v10, s[96:97]
	global_load_dwordx4 v[120:123], v11, s[96:97]
	global_load_dwordx4 v[124:127], v12, s[96:97]
	global_load_dwordx4 v[128:131], v13, s[96:97]
	ds_read2_b32 v[52:53], v15 offset0:0 offset1:33
	ds_read2_b32 v[54:55], v15 offset0:66 offset1:99
	ds_read2_b32 v[56:57], v15 offset0:132 offset1:165
	ds_read2_b32 v[58:59], v15 offset0:198 offset1:231
	ds_read2_b32 v[60:61], v15 offset0:8 offset1:41
	ds_read2_b32 v[62:63], v15 offset0:74 offset1:107
	ds_read2_b32 v[64:65], v15 offset0:140 offset1:173
	ds_read2_b32 v[66:67], v15 offset0:206 offset1:239
	ds_read2_b32 v[68:69], v15 offset0:16 offset1:49
	ds_read2_b32 v[70:71], v15 offset0:82 offset1:115
	ds_read2_b32 v[72:73], v15 offset0:148 offset1:181
	ds_read2_b32 v[74:75], v15 offset0:214 offset1:247
	ds_read2_b32 v[76:77], v15 offset0:24 offset1:57
	ds_read2_b32 v[78:79], v15 offset0:90 offset1:123
	ds_read2_b32 v[80:81], v15 offset0:156 offset1:189
	ds_read2_b32 v[82:83], v15 offset0:222 offset1:255
	s_add_u32 s95, s94, 0x3c00
	s_lshr_b32 vcc_lo, s95, 7
	s_and_b32 vcc_hi, s95, 0x7f
	s_mul_i32 vcc_hi, vcc_hi, 0xac000
	s_lshl_b32 vcc_lo, vcc_lo, 7
	s_add_u32 s98, s66, 0x12d00000
	s_addc_u32 s99, s67, 0
	s_add_u32 s98, s98, vcc_hi
	s_addc_u32 s99, s99, 0
	s_add_u32 s98, s98, vcc_lo
	s_addc_u32 s99, s99, 0
	s_waitcnt lgkmcnt(0)
	v_cvt_pk_bf16_f32 v84, v52, v53
	v_cvt_pk_bf16_f32 v85, v54, v55
	v_cvt_pk_bf16_f32 v86, v56, v57
	v_cvt_pk_bf16_f32 v87, v58, v59
	v_cvt_pk_bf16_f32 v88, v60, v61
	v_cvt_pk_bf16_f32 v89, v62, v63
	v_cvt_pk_bf16_f32 v90, v64, v65
	v_cvt_pk_bf16_f32 v91, v66, v67
	v_cvt_pk_bf16_f32 v92, v68, v69
	v_cvt_pk_bf16_f32 v93, v70, v71
	v_cvt_pk_bf16_f32 v94, v72, v73
	v_cvt_pk_bf16_f32 v95, v74, v75
	v_cvt_pk_bf16_f32 v96, v76, v77
	v_cvt_pk_bf16_f32 v97, v78, v79
	v_cvt_pk_bf16_f32 v98, v80, v81
	v_cvt_pk_bf16_f32 v99, v82, v83
	global_store_dwordx4 v16, v[84:87], s[98:99]
	global_store_dwordx4 v17, v[88:91], s[98:99]
	global_store_dwordx4 v18, v[92:95], s[98:99]
	global_store_dwordx4 v19, v[96:99], s[98:99]
	s_waitcnt vmcnt(23)
	ds_write_b32 v14, v20 offset:0
	ds_write_b32 v14, v21 offset:4
	ds_write_b32 v14, v22 offset:8
	ds_write_b32 v14, v23 offset:12
	s_waitcnt vmcnt(22)
	ds_write_b32 v14, v24 offset:1056
	ds_write_b32 v14, v25 offset:1060
	ds_write_b32 v14, v26 offset:1064
	ds_write_b32 v14, v27 offset:1068
	s_waitcnt vmcnt(21)
	ds_write_b32 v14, v28 offset:2112
	ds_write_b32 v14, v29 offset:2116
	ds_write_b32 v14, v30 offset:2120
	ds_write_b32 v14, v31 offset:2124
	s_waitcnt vmcnt(20)
	ds_write_b32 v14, v32 offset:3168
	ds_write_b32 v14, v33 offset:3172
	ds_write_b32 v14, v34 offset:3176
	ds_write_b32 v14, v35 offset:3180
	s_waitcnt vmcnt(19)
	ds_write_b32 v14, v36 offset:4224
	ds_write_b32 v14, v37 offset:4228
	ds_write_b32 v14, v38 offset:4232
	ds_write_b32 v14, v39 offset:4236
	s_waitcnt vmcnt(18)
	ds_write_b32 v14, v40 offset:5280
	ds_write_b32 v14, v41 offset:5284
	ds_write_b32 v14, v42 offset:5288
	ds_write_b32 v14, v43 offset:5292
	s_waitcnt vmcnt(17)
	ds_write_b32 v14, v44 offset:6336
	ds_write_b32 v14, v45 offset:6340
	ds_write_b32 v14, v46 offset:6344
	ds_write_b32 v14, v47 offset:6348
	s_waitcnt vmcnt(16)
	ds_write_b32 v14, v48 offset:7392
	ds_write_b32 v14, v49 offset:7396
	ds_write_b32 v14, v50 offset:7400
	ds_write_b32 v14, v51 offset:7404
	s_add_u32 s95, s94, 0x4800
	s_lshr_b32 vcc_lo, s95, 7
	s_and_b32 vcc_hi, s95, 0x7f
	s_lshl_b32 vcc_lo, vcc_lo, 20
	s_lshl_b32 vcc_hi, vcc_hi, 7
	s_add_u32 s96, s100, vcc_lo
	s_addc_u32 s97, s101, 0
	s_add_u32 s96, s96, vcc_hi
	s_addc_u32 s97, s97, 0
	global_load_dwordx4 v[20:23], v6, s[96:97]
	global_load_dwordx4 v[24:27], v7, s[96:97]
	global_load_dwordx4 v[28:31], v8, s[96:97]
	global_load_dwordx4 v[32:35], v9, s[96:97]
	global_load_dwordx4 v[36:39], v10, s[96:97]
	global_load_dwordx4 v[40:43], v11, s[96:97]
	global_load_dwordx4 v[44:47], v12, s[96:97]
	global_load_dwordx4 v[48:51], v13, s[96:97]
	ds_read2_b32 v[52:53], v15 offset0:0 offset1:33
	ds_read2_b32 v[54:55], v15 offset0:66 offset1:99
	ds_read2_b32 v[56:57], v15 offset0:132 offset1:165
	ds_read2_b32 v[58:59], v15 offset0:198 offset1:231
	ds_read2_b32 v[60:61], v15 offset0:8 offset1:41
	ds_read2_b32 v[62:63], v15 offset0:74 offset1:107
	ds_read2_b32 v[64:65], v15 offset0:140 offset1:173
	ds_read2_b32 v[66:67], v15 offset0:206 offset1:239
	ds_read2_b32 v[68:69], v15 offset0:16 offset1:49
	ds_read2_b32 v[70:71], v15 offset0:82 offset1:115
	ds_read2_b32 v[72:73], v15 offset0:148 offset1:181
	ds_read2_b32 v[74:75], v15 offset0:214 offset1:247
	ds_read2_b32 v[76:77], v15 offset0:24 offset1:57
	ds_read2_b32 v[78:79], v15 offset0:90 offset1:123
	ds_read2_b32 v[80:81], v15 offset0:156 offset1:189
	ds_read2_b32 v[82:83], v15 offset0:222 offset1:255
	s_add_u32 s95, s94, 0x4000
	s_lshr_b32 vcc_lo, s95, 7
	s_and_b32 vcc_hi, s95, 0x7f
	s_mul_i32 vcc_hi, vcc_hi, 0xac000
	s_lshl_b32 vcc_lo, vcc_lo, 7
	s_add_u32 s98, s66, 0x12d00000
	s_addc_u32 s99, s67, 0
	s_add_u32 s98, s98, vcc_hi
	s_addc_u32 s99, s99, 0
	s_add_u32 s98, s98, vcc_lo
	s_addc_u32 s99, s99, 0
	s_waitcnt lgkmcnt(0)
	v_cvt_pk_bf16_f32 v84, v52, v53
	v_cvt_pk_bf16_f32 v85, v54, v55
	v_cvt_pk_bf16_f32 v86, v56, v57
	v_cvt_pk_bf16_f32 v87, v58, v59
	v_cvt_pk_bf16_f32 v88, v60, v61
	v_cvt_pk_bf16_f32 v89, v62, v63
	v_cvt_pk_bf16_f32 v90, v64, v65
	v_cvt_pk_bf16_f32 v91, v66, v67
	v_cvt_pk_bf16_f32 v92, v68, v69
	v_cvt_pk_bf16_f32 v93, v70, v71
	v_cvt_pk_bf16_f32 v94, v72, v73
	v_cvt_pk_bf16_f32 v95, v74, v75
	v_cvt_pk_bf16_f32 v96, v76, v77
	v_cvt_pk_bf16_f32 v97, v78, v79
	v_cvt_pk_bf16_f32 v98, v80, v81
	v_cvt_pk_bf16_f32 v99, v82, v83
	global_store_dwordx4 v16, v[84:87], s[98:99]
	global_store_dwordx4 v17, v[88:91], s[98:99]
	global_store_dwordx4 v18, v[92:95], s[98:99]
	global_store_dwordx4 v19, v[96:99], s[98:99]
	s_waitcnt vmcnt(23)
	ds_write_b32 v14, v100 offset:0
	ds_write_b32 v14, v101 offset:4
	ds_write_b32 v14, v102 offset:8
	ds_write_b32 v14, v103 offset:12
	s_waitcnt vmcnt(22)
	ds_write_b32 v14, v104 offset:1056
	ds_write_b32 v14, v105 offset:1060
	ds_write_b32 v14, v106 offset:1064
	ds_write_b32 v14, v107 offset:1068
	s_waitcnt vmcnt(21)
	ds_write_b32 v14, v108 offset:2112
	ds_write_b32 v14, v109 offset:2116
	ds_write_b32 v14, v110 offset:2120
	ds_write_b32 v14, v111 offset:2124
	s_waitcnt vmcnt(20)
	ds_write_b32 v14, v112 offset:3168
	ds_write_b32 v14, v113 offset:3172
	ds_write_b32 v14, v114 offset:3176
	ds_write_b32 v14, v115 offset:3180
	s_waitcnt vmcnt(19)
	ds_write_b32 v14, v116 offset:4224
	ds_write_b32 v14, v117 offset:4228
	ds_write_b32 v14, v118 offset:4232
	ds_write_b32 v14, v119 offset:4236
	s_waitcnt vmcnt(18)
	ds_write_b32 v14, v120 offset:5280
	ds_write_b32 v14, v121 offset:5284
	ds_write_b32 v14, v122 offset:5288
	ds_write_b32 v14, v123 offset:5292
	s_waitcnt vmcnt(17)
	ds_write_b32 v14, v124 offset:6336
	ds_write_b32 v14, v125 offset:6340
	ds_write_b32 v14, v126 offset:6344
	ds_write_b32 v14, v127 offset:6348
	s_waitcnt vmcnt(16)
	ds_write_b32 v14, v128 offset:7392
	ds_write_b32 v14, v129 offset:7396
	ds_write_b32 v14, v130 offset:7400
	ds_write_b32 v14, v131 offset:7404
	s_add_u32 s95, s94, 0x4c00
	s_lshr_b32 vcc_lo, s95, 7
	s_and_b32 vcc_hi, s95, 0x7f
	s_lshl_b32 vcc_lo, vcc_lo, 20
	s_lshl_b32 vcc_hi, vcc_hi, 7
	s_add_u32 s96, s100, vcc_lo
	s_addc_u32 s97, s101, 0
	s_add_u32 s96, s96, vcc_hi
	s_addc_u32 s97, s97, 0
	global_load_dwordx4 v[100:103], v6, s[96:97]
	global_load_dwordx4 v[104:107], v7, s[96:97]
	global_load_dwordx4 v[108:111], v8, s[96:97]
	global_load_dwordx4 v[112:115], v9, s[96:97]
	global_load_dwordx4 v[116:119], v10, s[96:97]
	global_load_dwordx4 v[120:123], v11, s[96:97]
	global_load_dwordx4 v[124:127], v12, s[96:97]
	global_load_dwordx4 v[128:131], v13, s[96:97]
	ds_read2_b32 v[52:53], v15 offset0:0 offset1:33
	ds_read2_b32 v[54:55], v15 offset0:66 offset1:99
	ds_read2_b32 v[56:57], v15 offset0:132 offset1:165
	ds_read2_b32 v[58:59], v15 offset0:198 offset1:231
	ds_read2_b32 v[60:61], v15 offset0:8 offset1:41
	ds_read2_b32 v[62:63], v15 offset0:74 offset1:107
	ds_read2_b32 v[64:65], v15 offset0:140 offset1:173
	ds_read2_b32 v[66:67], v15 offset0:206 offset1:239
	ds_read2_b32 v[68:69], v15 offset0:16 offset1:49
	ds_read2_b32 v[70:71], v15 offset0:82 offset1:115
	ds_read2_b32 v[72:73], v15 offset0:148 offset1:181
	ds_read2_b32 v[74:75], v15 offset0:214 offset1:247
	ds_read2_b32 v[76:77], v15 offset0:24 offset1:57
	ds_read2_b32 v[78:79], v15 offset0:90 offset1:123
	ds_read2_b32 v[80:81], v15 offset0:156 offset1:189
	ds_read2_b32 v[82:83], v15 offset0:222 offset1:255
	s_add_u32 s95, s94, 0x4400
	s_lshr_b32 vcc_lo, s95, 7
	s_and_b32 vcc_hi, s95, 0x7f
	s_mul_i32 vcc_hi, vcc_hi, 0xac000
	s_lshl_b32 vcc_lo, vcc_lo, 7
	s_add_u32 s98, s66, 0x12d00000
	s_addc_u32 s99, s67, 0
	s_add_u32 s98, s98, vcc_hi
	s_addc_u32 s99, s99, 0
	s_add_u32 s98, s98, vcc_lo
	s_addc_u32 s99, s99, 0
	s_waitcnt lgkmcnt(0)
	v_cvt_pk_bf16_f32 v84, v52, v53
	v_cvt_pk_bf16_f32 v85, v54, v55
	v_cvt_pk_bf16_f32 v86, v56, v57
	v_cvt_pk_bf16_f32 v87, v58, v59
	v_cvt_pk_bf16_f32 v88, v60, v61
	v_cvt_pk_bf16_f32 v89, v62, v63
	v_cvt_pk_bf16_f32 v90, v64, v65
	v_cvt_pk_bf16_f32 v91, v66, v67
	v_cvt_pk_bf16_f32 v92, v68, v69
	v_cvt_pk_bf16_f32 v93, v70, v71
	v_cvt_pk_bf16_f32 v94, v72, v73
	v_cvt_pk_bf16_f32 v95, v74, v75
	v_cvt_pk_bf16_f32 v96, v76, v77
	v_cvt_pk_bf16_f32 v97, v78, v79
	v_cvt_pk_bf16_f32 v98, v80, v81
	v_cvt_pk_bf16_f32 v99, v82, v83
	global_store_dwordx4 v16, v[84:87], s[98:99]
	global_store_dwordx4 v17, v[88:91], s[98:99]
	global_store_dwordx4 v18, v[92:95], s[98:99]
	global_store_dwordx4 v19, v[96:99], s[98:99]
	s_waitcnt vmcnt(23)
	ds_write_b32 v14, v20 offset:0
	ds_write_b32 v14, v21 offset:4
	ds_write_b32 v14, v22 offset:8
	ds_write_b32 v14, v23 offset:12
	s_waitcnt vmcnt(22)
	ds_write_b32 v14, v24 offset:1056
	ds_write_b32 v14, v25 offset:1060
	ds_write_b32 v14, v26 offset:1064
	ds_write_b32 v14, v27 offset:1068
	s_waitcnt vmcnt(21)
	ds_write_b32 v14, v28 offset:2112
	ds_write_b32 v14, v29 offset:2116
	ds_write_b32 v14, v30 offset:2120
	ds_write_b32 v14, v31 offset:2124
	s_waitcnt vmcnt(20)
	ds_write_b32 v14, v32 offset:3168
	ds_write_b32 v14, v33 offset:3172
	ds_write_b32 v14, v34 offset:3176
	ds_write_b32 v14, v35 offset:3180
	s_waitcnt vmcnt(19)
	ds_write_b32 v14, v36 offset:4224
	ds_write_b32 v14, v37 offset:4228
	ds_write_b32 v14, v38 offset:4232
	ds_write_b32 v14, v39 offset:4236
	s_waitcnt vmcnt(18)
	ds_write_b32 v14, v40 offset:5280
	ds_write_b32 v14, v41 offset:5284
	ds_write_b32 v14, v42 offset:5288
	ds_write_b32 v14, v43 offset:5292
	s_waitcnt vmcnt(17)
	ds_write_b32 v14, v44 offset:6336
	ds_write_b32 v14, v45 offset:6340
	ds_write_b32 v14, v46 offset:6344
	ds_write_b32 v14, v47 offset:6348
	s_waitcnt vmcnt(16)
	ds_write_b32 v14, v48 offset:7392
	ds_write_b32 v14, v49 offset:7396
	ds_write_b32 v14, v50 offset:7400
	ds_write_b32 v14, v51 offset:7404
	ds_read2_b32 v[52:53], v15 offset0:0 offset1:33
	ds_read2_b32 v[54:55], v15 offset0:66 offset1:99
	ds_read2_b32 v[56:57], v15 offset0:132 offset1:165
	ds_read2_b32 v[58:59], v15 offset0:198 offset1:231
	ds_read2_b32 v[60:61], v15 offset0:8 offset1:41
	ds_read2_b32 v[62:63], v15 offset0:74 offset1:107
	ds_read2_b32 v[64:65], v15 offset0:140 offset1:173
	ds_read2_b32 v[66:67], v15 offset0:206 offset1:239
	ds_read2_b32 v[68:69], v15 offset0:16 offset1:49
	ds_read2_b32 v[70:71], v15 offset0:82 offset1:115
	ds_read2_b32 v[72:73], v15 offset0:148 offset1:181
	ds_read2_b32 v[74:75], v15 offset0:214 offset1:247
	ds_read2_b32 v[76:77], v15 offset0:24 offset1:57
	ds_read2_b32 v[78:79], v15 offset0:90 offset1:123
	ds_read2_b32 v[80:81], v15 offset0:156 offset1:189
	ds_read2_b32 v[82:83], v15 offset0:222 offset1:255
	s_add_u32 s95, s94, 0x4800
	s_lshr_b32 vcc_lo, s95, 7
	s_and_b32 vcc_hi, s95, 0x7f
	s_mul_i32 vcc_hi, vcc_hi, 0xac000
	s_lshl_b32 vcc_lo, vcc_lo, 7
	s_add_u32 s98, s66, 0x12d00000
	s_addc_u32 s99, s67, 0
	s_add_u32 s98, s98, vcc_hi
	s_addc_u32 s99, s99, 0
	s_add_u32 s98, s98, vcc_lo
	s_addc_u32 s99, s99, 0
	s_waitcnt lgkmcnt(0)
	v_cvt_pk_bf16_f32 v84, v52, v53
	v_cvt_pk_bf16_f32 v85, v54, v55
	v_cvt_pk_bf16_f32 v86, v56, v57
	v_cvt_pk_bf16_f32 v87, v58, v59
	v_cvt_pk_bf16_f32 v88, v60, v61
	v_cvt_pk_bf16_f32 v89, v62, v63
	v_cvt_pk_bf16_f32 v90, v64, v65
	v_cvt_pk_bf16_f32 v91, v66, v67
	v_cvt_pk_bf16_f32 v92, v68, v69
	v_cvt_pk_bf16_f32 v93, v70, v71
	v_cvt_pk_bf16_f32 v94, v72, v73
	v_cvt_pk_bf16_f32 v95, v74, v75
	v_cvt_pk_bf16_f32 v96, v76, v77
	v_cvt_pk_bf16_f32 v97, v78, v79
	v_cvt_pk_bf16_f32 v98, v80, v81
	v_cvt_pk_bf16_f32 v99, v82, v83
	global_store_dwordx4 v16, v[84:87], s[98:99]
	global_store_dwordx4 v17, v[88:91], s[98:99]
	global_store_dwordx4 v18, v[92:95], s[98:99]
	global_store_dwordx4 v19, v[96:99], s[98:99]
	s_waitcnt vmcnt(15)
	ds_write_b32 v14, v100 offset:0
	ds_write_b32 v14, v101 offset:4
	ds_write_b32 v14, v102 offset:8
	ds_write_b32 v14, v103 offset:12
	s_waitcnt vmcnt(14)
	ds_write_b32 v14, v104 offset:1056
	ds_write_b32 v14, v105 offset:1060
	ds_write_b32 v14, v106 offset:1064
	ds_write_b32 v14, v107 offset:1068
	s_waitcnt vmcnt(13)
	ds_write_b32 v14, v108 offset:2112
	ds_write_b32 v14, v109 offset:2116
	ds_write_b32 v14, v110 offset:2120
	ds_write_b32 v14, v111 offset:2124
	s_waitcnt vmcnt(12)
	ds_write_b32 v14, v112 offset:3168
	ds_write_b32 v14, v113 offset:3172
	ds_write_b32 v14, v114 offset:3176
	ds_write_b32 v14, v115 offset:3180
	s_waitcnt vmcnt(11)
	ds_write_b32 v14, v116 offset:4224
	ds_write_b32 v14, v117 offset:4228
	ds_write_b32 v14, v118 offset:4232
	ds_write_b32 v14, v119 offset:4236
	s_waitcnt vmcnt(10)
	ds_write_b32 v14, v120 offset:5280
	ds_write_b32 v14, v121 offset:5284
	ds_write_b32 v14, v122 offset:5288
	ds_write_b32 v14, v123 offset:5292
	s_waitcnt vmcnt(9)
	ds_write_b32 v14, v124 offset:6336
	ds_write_b32 v14, v125 offset:6340
	ds_write_b32 v14, v126 offset:6344
	ds_write_b32 v14, v127 offset:6348
	s_waitcnt vmcnt(8)
	ds_write_b32 v14, v128 offset:7392
	ds_write_b32 v14, v129 offset:7396
	ds_write_b32 v14, v130 offset:7400
	ds_write_b32 v14, v131 offset:7404
	ds_read2_b32 v[52:53], v15 offset0:0 offset1:33
	ds_read2_b32 v[54:55], v15 offset0:66 offset1:99
	ds_read2_b32 v[56:57], v15 offset0:132 offset1:165
	ds_read2_b32 v[58:59], v15 offset0:198 offset1:231
	ds_read2_b32 v[60:61], v15 offset0:8 offset1:41
	ds_read2_b32 v[62:63], v15 offset0:74 offset1:107
	ds_read2_b32 v[64:65], v15 offset0:140 offset1:173
	ds_read2_b32 v[66:67], v15 offset0:206 offset1:239
	ds_read2_b32 v[68:69], v15 offset0:16 offset1:49
	ds_read2_b32 v[70:71], v15 offset0:82 offset1:115
	ds_read2_b32 v[72:73], v15 offset0:148 offset1:181
	ds_read2_b32 v[74:75], v15 offset0:214 offset1:247
	ds_read2_b32 v[76:77], v15 offset0:24 offset1:57
	ds_read2_b32 v[78:79], v15 offset0:90 offset1:123
	ds_read2_b32 v[80:81], v15 offset0:156 offset1:189
	ds_read2_b32 v[82:83], v15 offset0:222 offset1:255
	s_add_u32 s95, s94, 0x4c00
	s_lshr_b32 vcc_lo, s95, 7
	s_and_b32 vcc_hi, s95, 0x7f
	s_mul_i32 vcc_hi, vcc_hi, 0xac000
	s_lshl_b32 vcc_lo, vcc_lo, 7
	s_add_u32 s98, s66, 0x12d00000
	s_addc_u32 s99, s67, 0
	s_add_u32 s98, s98, vcc_hi
	s_addc_u32 s99, s99, 0
	s_add_u32 s98, s98, vcc_lo
	s_addc_u32 s99, s99, 0
	s_waitcnt lgkmcnt(0)
	v_cvt_pk_bf16_f32 v84, v52, v53
	v_cvt_pk_bf16_f32 v85, v54, v55
	v_cvt_pk_bf16_f32 v86, v56, v57
	v_cvt_pk_bf16_f32 v87, v58, v59
	v_cvt_pk_bf16_f32 v88, v60, v61
	v_cvt_pk_bf16_f32 v89, v62, v63
	v_cvt_pk_bf16_f32 v90, v64, v65
	v_cvt_pk_bf16_f32 v91, v66, v67
	v_cvt_pk_bf16_f32 v92, v68, v69
	v_cvt_pk_bf16_f32 v93, v70, v71
	v_cvt_pk_bf16_f32 v94, v72, v73
	v_cvt_pk_bf16_f32 v95, v74, v75
	v_cvt_pk_bf16_f32 v96, v76, v77
	v_cvt_pk_bf16_f32 v97, v78, v79
	v_cvt_pk_bf16_f32 v98, v80, v81
	v_cvt_pk_bf16_f32 v99, v82, v83
	global_store_dwordx4 v16, v[84:87], s[98:99]
	global_store_dwordx4 v17, v[88:91], s[98:99]
	global_store_dwordx4 v18, v[92:95], s[98:99]
	global_store_dwordx4 v19, v[96:99], s[98:99]
